# prep phase: bf16 field stores use SGPR base + 32-bit VGPR offset addressing (88 per-store 64-bit address adds removed)
# speedup vs baseline: 1.0023x; 1.0023x over previous
.LBB0_301:
	s_or_b64 exec, exec, s[44:45]
	v_and_b32_e32 v52, 15, v111
	v_bfe_u32 v55, v111, 4, 2
	v_mul_u32_u24_e32 v56, 0xe10, v52
	v_lshlrev_b32_e32 v57, 5, v55
	v_add3_u32 v80, 0, v56, v57
	s_waitcnt lgkmcnt(0)
	s_barrier
	ds_read_b128 v[56:59], v80 offset:3072
	ds_read_b128 v[60:63], v80 offset:3088
	s_waitcnt lgkmcnt(1)
	v_cvt_pk_bf16_f32 v56, v56, v57
	v_cvt_pk_bf16_f32 v57, v58, v59
	s_waitcnt lgkmcnt(0)
	v_cvt_pk_bf16_f32 v58, v60, v61
	v_cvt_pk_bf16_f32 v59, v62, v63
	ds_read_b128 v[60:63], v80 offset:3200
	ds_read_b128 v[64:67], v80 offset:3216
	s_waitcnt lgkmcnt(1)
	v_cvt_pk_bf16_f32 v60, v60, v61
	v_cvt_pk_bf16_f32 v61, v62, v63
	s_waitcnt lgkmcnt(0)
	v_cvt_pk_bf16_f32 v62, v64, v65
	v_cvt_pk_bf16_f32 v63, v66, v67
	ds_read_b128 v[64:67], v80 offset:3328
	ds_read_b128 v[68:71], v80 offset:3344
	s_waitcnt lgkmcnt(1)
	v_cvt_pk_bf16_f32 v64, v64, v65
	v_cvt_pk_bf16_f32 v65, v66, v67
	s_waitcnt lgkmcnt(0)
	v_cvt_pk_bf16_f32 v66, v68, v69
	v_cvt_pk_bf16_f32 v67, v70, v71
	v_mfma_f32_16x16x32_bf16 v[72:75], v[56:59], v[18:21], 0
	ds_read_b128 v[68:71], v80 offset:3456
	ds_read_b128 v[80:83], v80 offset:3472
	v_lshl_add_u32 v55, v55, 12, 0
	v_mfma_f32_16x16x32_bf16 v[84:87], v[64:67], v[26:29], 0
	v_and_b32_e32 v54, 0xffffff80, v54
	v_lshlrev_b32_e32 v52, 2, v52
	s_waitcnt lgkmcnt(1)
	v_cvt_pk_bf16_f32 v68, v68, v69
	v_mfma_f32_16x16x32_bf16 v[64:67], v[64:67], v[42:45], 0
	v_cvt_pk_bf16_f32 v69, v70, v71
	s_waitcnt lgkmcnt(0)
	v_cvt_pk_bf16_f32 v70, v80, v81
	v_cvt_pk_bf16_f32 v71, v82, v83
	v_mfma_f32_16x16x32_bf16 v[56:59], v[56:59], v[34:37], 0
	v_add3_u32 v52, v55, v54, v52
	v_add_u32_e32 v54, 0xe900, v52
	v_add_u32_e32 v55, 0xe800, v52
	v_mfma_f32_16x16x32_bf16 v[76:79], v[60:63], v[22:25], 0
	s_ashr_i32 s37, s36, 31
	s_nop 2
	ds_write2_b32 v55, v72, v56 offset0:64 offset1:80
	v_add_u32_e32 v55, 0x4000, v54
	v_mfma_f32_16x16x32_bf16 v[60:63], v[60:63], v[38:41], 0
	v_lshlrev_b32_sdwa v72, v17, v111 dst_sel:DWORD dst_unused:UNUSED_PAD src0_sel:DWORD src1_sel:BYTE_0
	v_and_b32_e32 v102, 63, v111
	v_mfma_f32_16x16x32_bf16 v[80:83], v[68:71], v[30:33], v[84:87]
	v_mfma_f32_16x16x32_bf16 v[64:67], v[68:71], v[46:49], v[64:67]
	s_nop 3
	ds_write2_b32 v55, v76, v60 offset1:16
	v_add_u32_e32 v55, 0x8000, v54
	v_ashrrev_i32_e32 v70, 8, v111
	v_lshlrev_b32_e32 v118, 3, v70
	v_ashrrev_i32_e32 v119, 31, v118
	ds_write2_b32 v55, v80, v64 offset1:16
	v_add_u32_e32 v55, 0xc000, v54
	ds_write2_b32 v55, v53, v53 offset1:16
	v_add_u32_e32 v55, 0xec00, v52
	ds_write2_b32 v55, v73, v57 offset0:64 offset1:80
	v_add_u32_e32 v55, 0x4400, v54
	ds_write2_b32 v55, v77, v61 offset1:16
	v_add_u32_e32 v55, 0x8400, v54
	ds_write2_b32 v55, v81, v65 offset1:16
	v_add_u32_e32 v55, 0xc400, v54
	ds_write2_b32 v55, v53, v53 offset1:16
	v_add_u32_e32 v55, 0xf000, v52
	v_add_u32_e32 v52, 0xf400, v52
	ds_write2_b32 v52, v75, v59 offset0:64 offset1:80
	v_add_u32_e32 v52, 0x4c00, v54
	ds_write2_b32 v52, v79, v63 offset1:16
	v_add_u32_e32 v52, 0x8c00, v54
	ds_write2_b32 v52, v83, v67 offset1:16
	v_add_u32_e32 v52, 0xcc00, v54
	ds_write2_b32 v55, v74, v58 offset0:64 offset1:80
	v_add_u32_e32 v55, 0x4800, v54
	ds_write2_b32 v52, v53, v53 offset1:16
	v_lshlrev_b32_e32 v52, 13, v70
	ds_write2_b32 v55, v78, v62 offset1:16
	v_add_u32_e32 v55, 0x8800, v54
	v_add3_u32 v52, 0, v52, v72
	ds_write2_b32 v55, v82, v66 offset1:16
	v_add_u32_e32 v55, 0xc800, v54
	v_add_u32_e32 v54, 0xe900, v52
	ds_write2_b32 v55, v53, v53 offset1:16
	s_waitcnt lgkmcnt(0)
	s_barrier
	ds_read2st64_b32 v[90:91], v52 offset0:233 offset1:237
	ds_read2st64_b32 v[62:63], v54 offset0:64 offset1:68
	ds_read2st64_b32 v[84:85], v54 offset0:128 offset1:132
	ds_read2st64_b32 v[74:75], v52 offset0:241 offset1:245
	ds_read2st64_b32 v[66:67], v54 offset0:72 offset1:76
	ds_read2st64_b32 v[64:65], v54 offset0:136 offset1:140
	ds_read2st64_b32 v[60:61], v52 offset0:249 offset1:253
	ds_read2st64_b32 v[68:69], v54 offset0:80 offset1:84
	ds_read2st64_b32 v[58:59], v54 offset0:144 offset1:148
	ds_read2st64_b32 v[56:57], v54 offset0:24 offset1:28
	ds_read2st64_b32 v[124:125], v54 offset0:88 offset1:92
	ds_read2st64_b32 v[54:55], v54 offset0:152 offset1:156
	s_waitcnt vmcnt(4) lgkmcnt(11)
	v_add_f32_e32 v71, v104, v90
	v_mul_f32_e32 v71, 0xbfb8aa3b, v71
	v_exp_f32_e32 v71, v71
	v_lshlrev_b32_sdwa v52, v109, v111 dst_sel:DWORD dst_unused:UNUSED_PAD src0_sel:DWORD src1_sel:BYTE_0
	v_lshl_add_u64 v[134:135], s[20:21], 0, v[52:53]
	s_waitcnt vmcnt(3) lgkmcnt(10)
	v_add_f32_e32 v62, v105, v62
	v_add_f32_e32 v52, 1.0, v71
	v_rcp_f32_e32 v52, v52
	v_mul_f32_e32 v62, 0xbfb8aa3b, v62
	v_exp_f32_e32 v62, v62
	v_mul_i32_i24_e32 v70, 0x7080, v70
	v_mul_f32_e32 v52, 0xbf1b4598, v52
	v_mul_f32_e32 v52, 0x3fb8aa3b, v52
	v_exp_f32_e32 v120, v52
	v_add_f32_e32 v52, 1.0, v62
	v_add3_u32 v70, 0, v70, v72
	v_rcp_f32_e32 v52, v52
	v_lshl_add_u64 v[96:97], v[118:119], 0, s[36:37]
	ds_read2st64_b32 v[100:101], v70 offset1:4
	ds_read_b32 v90, v70 offset:2048
	v_lshlrev_b64 v[70:71], 9, v[96:97]
	v_lshl_add_u64 v[70:71], v[134:135], 0, v[70:71]
	s_waitcnt lgkmcnt(0)
	v_cvt_pk_bf16_f32 v62, v90, v53
	global_store_short v[70:71], v62, off
	v_add_f32_e32 v62, -1.0, v52
	s_waitcnt vmcnt(2)
	v_fma_f32 v62, v107, v62, 1.0
	v_or_b32_e32 v70, 1, v118
	v_mul_f32_e32 v132, v62, v101
	v_mul_lo_u32 v62, v70, s61
	v_add3_u32 v123, 0, v62, v72
	v_add_f32_e32 v62, v105, v63
	v_mul_f32_e32 v62, 0xbfb8aa3b, v62
	v_exp_f32_e32 v62, v62
	v_ashrrev_i32_e32 v71, 31, v70
	v_lshl_add_u64 v[94:95], v[70:71], 0, s[36:37]
	ds_read2st64_b32 v[98:99], v123 offset1:4
	v_add_f32_e32 v62, 1.0, v62
	v_rcp_f32_e32 v127, v62
	v_lshlrev_b64 v[62:63], 9, v[94:95]
	v_lshl_add_u64 v[62:63], v[134:135], 0, v[62:63]
	ds_read_b32 v122, v123 offset:2048
	s_waitcnt lgkmcnt(0)
	v_cvt_pk_bf16_f32 v70, v122, v53
	global_store_short v[62:63], v70, off
	v_add_f32_e32 v62, -1.0, v127
	v_fma_f32 v62, v107, v62, 1.0
	v_mul_f32_e32 v126, v62, v99
	v_or_b32_e32 v62, 2, v118
	v_ashrrev_i32_e32 v63, 31, v62
	v_lshl_add_u64 v[86:87], v[62:63], 0, s[36:37]
	v_add_f32_e32 v62, v105, v66
	v_mul_f32_e32 v62, 0xbfb8aa3b, v62
	v_exp_f32_e32 v62, v62
	v_add_u32_e32 v63, 16, v123
	ds_read2st64_b32 v[92:93], v63 offset0:14 offset1:18
	ds_read_b32 v117, v123 offset:5648
	v_add_f32_e32 v62, 1.0, v62
	v_rcp_f32_e32 v137, v62
	v_lshlrev_b64 v[62:63], 9, v[86:87]
	v_lshl_add_u64 v[62:63], v[134:135], 0, v[62:63]
	s_waitcnt lgkmcnt(0)
	v_cvt_pk_bf16_f32 v66, v117, v53
	global_store_short v[62:63], v66, off
	v_add_f32_e32 v62, -1.0, v137
	v_fma_f32 v62, v107, v62, 1.0
	v_mul_f32_e32 v121, v62, v93
	v_or_b32_e32 v62, 3, v118
	v_ashrrev_i32_e32 v63, 31, v62
	v_lshl_add_u64 v[80:81], v[62:63], 0, s[36:37]
	v_add_f32_e32 v62, v105, v67
	v_mul_f32_e32 v62, 0xbfb8aa3b, v62
	v_exp_f32_e32 v62, v62
	v_add_u32_e32 v63, 32, v123
	ds_read2st64_b32 v[88:89], v63 offset0:28 offset1:32
	ds_read_b32 v114, v123 offset:9248
	v_add_f32_e32 v62, 1.0, v62
	v_rcp_f32_e32 v119, v62
	v_lshlrev_b64 v[62:63], 9, v[80:81]
	v_lshl_add_u64 v[62:63], v[134:135], 0, v[62:63]
	s_waitcnt lgkmcnt(0)
	v_cvt_pk_bf16_f32 v66, v114, v53
	global_store_short v[62:63], v66, off
	v_add_f32_e32 v62, -1.0, v119
	v_fma_f32 v62, v107, v62, 1.0
	v_mul_f32_e32 v116, v62, v89
	v_or_b32_e32 v62, 4, v118
	v_ashrrev_i32_e32 v63, 31, v62
	v_lshl_add_u64 v[76:77], v[62:63], 0, s[36:37]
	v_add_f32_e32 v62, v105, v68
	v_mul_f32_e32 v62, 0xbfb8aa3b, v62
	v_exp_f32_e32 v62, v62
	v_add_u32_e32 v63, 48, v123
	ds_read2st64_b32 v[82:83], v63 offset0:42 offset1:46
	v_mul_f32_e32 v103, v106, v101
	v_add_f32_e32 v62, 1.0, v62
	v_rcp_f32_e32 v142, v62
	v_lshlrev_b64 v[62:63], 9, v[76:77]
	v_lshl_add_u64 v[62:63], v[134:135], 0, v[62:63]
	ds_read_b32 v101, v123 offset:12848
	s_waitcnt lgkmcnt(0)
	v_cvt_pk_bf16_f32 v66, v101, v53
	global_store_short v[62:63], v66, off
	v_add_f32_e32 v62, -1.0, v142
	v_fma_f32 v62, v107, v62, 1.0
	v_mul_f32_e32 v113, v62, v83
	v_or_b32_e32 v62, 5, v118
	v_ashrrev_i32_e32 v63, 31, v62
	v_lshl_add_u64 v[70:71], v[62:63], 0, s[36:37]
	v_add_f32_e32 v62, v105, v69
	v_mul_f32_e32 v62, 0xbfb8aa3b, v62
	v_exp_f32_e32 v62, v62
	v_add_u32_e32 v63, 64, v123
	ds_read2st64_b32 v[78:79], v63 offset0:56 offset1:60
	v_mul_f32_e32 v138, v106, v93
	v_add_f32_e32 v62, 1.0, v62
	v_rcp_f32_e32 v112, v62
	v_lshlrev_b64 v[62:63], 9, v[70:71]
	v_lshl_add_u64 v[62:63], v[134:135], 0, v[62:63]
	ds_read_b32 v93, v123 offset:16448
	s_waitcnt lgkmcnt(0)
	v_cvt_pk_bf16_f32 v66, v93, v53
	global_store_short v[62:63], v66, off
	v_add_f32_e32 v62, -1.0, v112
	v_fma_f32 v62, v107, v62, 1.0
	v_mul_f32_e32 v133, v106, v99
	v_mul_f32_e32 v99, v62, v79
	v_or_b32_e32 v62, 6, v118
	v_ashrrev_i32_e32 v63, 31, v62
	v_lshl_add_u64 v[66:67], v[62:63], 0, s[36:37]
	v_add_f32_e32 v62, v105, v124
	v_mul_f32_e32 v62, 0xbfb8aa3b, v62
	v_exp_f32_e32 v62, v62
	v_add_u32_e32 v63, 0x50, v123
	ds_read2st64_b32 v[72:73], v63 offset0:70 offset1:74
	v_mul_f32_e32 v145, v106, v79
	v_add_f32_e32 v62, 1.0, v62
	v_rcp_f32_e32 v148, v62
	v_lshlrev_b64 v[62:63], 9, v[66:67]
	v_lshl_add_u64 v[62:63], v[134:135], 0, v[62:63]
	ds_read_b32 v79, v123 offset:20048
	s_waitcnt lgkmcnt(0)
	v_cvt_pk_bf16_f32 v68, v79, v53
	global_store_short v[62:63], v68, off
	v_add_f32_e32 v62, -1.0, v148
	v_fma_f32 v62, v107, v62, 1.0
	v_mul_f32_e32 v140, v106, v89
	v_mul_f32_e32 v89, v62, v73
	v_or_b32_e32 v62, 7, v118
	v_ashrrev_i32_e32 v63, 31, v62
	v_lshl_add_u64 v[62:63], v[62:63], 0, s[36:37]
	v_add_f32_e32 v68, v105, v125
	v_mul_f32_e32 v68, 0xbfb8aa3b, v68
	v_lshlrev_b64 v[124:125], 9, v[62:63]
	v_mul_f32_e32 v136, v133, v133
	v_mul_f32_e32 v143, v106, v83
	v_exp_f32_e32 v83, v68
	v_add_u32_e32 v68, 0x60, v123
	v_lshl_add_u64 v[124:125], v[134:135], 0, v[124:125]
	v_mul_f32_e32 v149, v106, v73
	ds_read_b32 v73, v123 offset:23648
	ds_read2st64_b32 v[68:69], v68 offset0:84 offset1:88
	s_waitcnt lgkmcnt(1)
	v_cvt_pk_bf16_f32 v118, v73, v53
	global_store_short v[124:125], v118, off
	v_and_b32_e32 v125, 64, v110
	v_mov_b32_dpp v135, v136 quad_perm:[1,0,3,2] row_mask:0xf bank_mask:0xf bound_ctrl:1
	v_xor_b32_e32 v124, 16, v110
	v_add_u32_e32 v125, 64, v125
	v_fmac_f32_e32 v135, v133, v133
	v_cmp_lt_i32_e32 vcc, v124, v125
	v_mul_f32_e32 v115, v103, v103
	v_add_f32_dpp v135, v135, v135 quad_perm:[2,3,0,1] row_mask:0xf bank_mask:0xf bound_ctrl:1
	v_cndmask_b32_e32 v124, v110, v124, vcc
	v_lshlrev_b32_e32 v151, 2, v124
	v_add_f32_dpp v135, v135, v135 row_half_mirror row_mask:0xf bank_mask:0xf bound_ctrl:1
	v_mul_f32_e32 v139, v138, v138
	v_xor_b32_e32 v124, 32, v110
	v_add_f32_dpp v135, v135, v135 row_mirror row_mask:0xf bank_mask:0xf bound_ctrl:1
	ds_bpermute_b32 v136, v151, v135
	v_mov_b32_dpp v115, v115 quad_perm:[1,0,3,2] row_mask:0xf bank_mask:0xf bound_ctrl:1
	v_cmp_lt_i32_e32 vcc, v124, v125
	v_fmac_f32_e32 v115, v103, v103
	v_add_f32_e32 v83, 1.0, v83
	s_waitcnt lgkmcnt(0)
	v_add_f32_e32 v125, v135, v136
	v_mov_b32_dpp v135, v139 quad_perm:[1,0,3,2] row_mask:0xf bank_mask:0xf bound_ctrl:1
	v_fmac_f32_e32 v135, v138, v138
	v_add_f32_dpp v115, v115, v115 quad_perm:[2,3,0,1] row_mask:0xf bank_mask:0xf bound_ctrl:1
	v_mul_f32_e32 v141, v140, v140
	v_add_f32_dpp v135, v135, v135 quad_perm:[2,3,0,1] row_mask:0xf bank_mask:0xf bound_ctrl:1
	v_add_f32_dpp v115, v115, v115 row_half_mirror row_mask:0xf bank_mask:0xf bound_ctrl:1
	v_rcp_f32_e32 v83, v83
	v_add_f32_dpp v135, v135, v135 row_half_mirror row_mask:0xf bank_mask:0xf bound_ctrl:1
	v_add_f32_dpp v115, v115, v115 row_mirror row_mask:0xf bank_mask:0xf bound_ctrl:1
	ds_bpermute_b32 v134, v151, v115
	v_add_f32_dpp v135, v135, v135 row_mirror row_mask:0xf bank_mask:0xf bound_ctrl:1
	ds_bpermute_b32 v136, v151, v135
	v_mov_b32_dpp v139, v141 quad_perm:[1,0,3,2] row_mask:0xf bank_mask:0xf bound_ctrl:1
	v_fmac_f32_e32 v139, v140, v140
	v_add_f32_e32 v123, -1.0, v83
	v_mul_f32_e32 v144, v143, v143
	v_add_f32_dpp v139, v139, v139 quad_perm:[2,3,0,1] row_mask:0xf bank_mask:0xf bound_ctrl:1
	v_mul_f32_e32 v118, v106, v69
	v_fma_f32 v123, v107, v123, 1.0
	v_add_f32_dpp v139, v139, v139 row_half_mirror row_mask:0xf bank_mask:0xf bound_ctrl:1
	v_cndmask_b32_e32 v124, v110, v124, vcc
	v_mul_f32_e32 v69, v123, v69
	v_add_f32_dpp v139, v139, v139 row_mirror row_mask:0xf bank_mask:0xf bound_ctrl:1
	v_mul_f32_e32 v123, v118, v118
	v_lshlrev_b32_e32 v173, 2, v124
	s_waitcnt lgkmcnt(1)
	v_add_f32_e32 v115, v115, v134
	ds_bpermute_b32 v141, v151, v139
	v_mov_b32_dpp v144, v144 quad_perm:[1,0,3,2] row_mask:0xf bank_mask:0xf bound_ctrl:1
	s_waitcnt lgkmcnt(1)
	v_add_f32_e32 v135, v135, v136
	ds_bpermute_b32 v124, v173, v115
	ds_bpermute_b32 v134, v173, v125
	v_fmac_f32_e32 v144, v143, v143
	ds_bpermute_b32 v136, v173, v135
	v_mov_b32_dpp v123, v123 quad_perm:[1,0,3,2] row_mask:0xf bank_mask:0xf bound_ctrl:1
	v_add_f32_dpp v144, v144, v144 quad_perm:[2,3,0,1] row_mask:0xf bank_mask:0xf bound_ctrl:1
	v_fmac_f32_e32 v123, v118, v118
	v_mul_f32_e32 v146, v145, v145
	v_add_f32_dpp v144, v144, v144 row_half_mirror row_mask:0xf bank_mask:0xf bound_ctrl:1
	v_add_f32_dpp v123, v123, v123 quad_perm:[2,3,0,1] row_mask:0xf bank_mask:0xf bound_ctrl:1
	s_waitcnt lgkmcnt(3)
	v_add_f32_e32 v139, v139, v141
	v_add_f32_dpp v144, v144, v144 row_mirror row_mask:0xf bank_mask:0xf bound_ctrl:1
	v_add_f32_dpp v123, v123, v123 row_half_mirror row_mask:0xf bank_mask:0xf bound_ctrl:1
	ds_bpermute_b32 v150, v151, v144
	ds_bpermute_b32 v141, v173, v139
	v_add_f32_dpp v123, v123, v123 row_mirror row_mask:0xf bank_mask:0xf bound_ctrl:1
	s_waitcnt lgkmcnt(4)
	v_add_f32_e32 v115, v115, v124
	s_waitcnt lgkmcnt(3)
	v_add_f32_e32 v124, v125, v134
	s_waitcnt lgkmcnt(2)
	v_add_f32_e32 v125, v135, v136
	v_mov_b32_dpp v136, v146 quad_perm:[1,0,3,2] row_mask:0xf bank_mask:0xf bound_ctrl:1
	ds_bpermute_b32 v146, v151, v123
	v_mul_f32_e32 v147, v149, v149
	s_waitcnt lgkmcnt(2)
	v_add_f32_e32 v144, v144, v150
	ds_bpermute_b32 v150, v173, v144
	s_waitcnt lgkmcnt(2)
	v_add_f32_e32 v134, v139, v141
	v_mov_b32_dpp v141, v147 quad_perm:[1,0,3,2] row_mask:0xf bank_mask:0xf bound_ctrl:1
	s_waitcnt lgkmcnt(1)
	v_add_f32_e32 v123, v123, v146
	v_fmac_f32_e32 v136, v145, v145
	v_fmac_f32_e32 v141, v149, v149
	ds_bpermute_b32 v146, v173, v123
	v_add_f32_dpp v136, v136, v136 quad_perm:[2,3,0,1] row_mask:0xf bank_mask:0xf bound_ctrl:1
	v_add_f32_dpp v141, v141, v141 quad_perm:[2,3,0,1] row_mask:0xf bank_mask:0xf bound_ctrl:1
	v_max_f32_e32 v115, 0x179abe15, v115
	v_add_f32_dpp v136, v136, v136 row_half_mirror row_mask:0xf bank_mask:0xf bound_ctrl:1
	v_add_f32_dpp v141, v141, v141 row_half_mirror row_mask:0xf bank_mask:0xf bound_ctrl:1
	s_waitcnt lgkmcnt(1)
	v_add_f32_e32 v135, v144, v150
	v_add_f32_dpp v136, v136, v136 row_mirror row_mask:0xf bank_mask:0xf bound_ctrl:1
	v_add_f32_dpp v141, v141, v141 row_mirror row_mask:0xf bank_mask:0xf bound_ctrl:1
	ds_bpermute_b32 v139, v151, v136
	ds_bpermute_b32 v144, v151, v141
	v_rsq_f32_e32 v115, v115
	s_waitcnt lgkmcnt(2)
	v_add_f32_e32 v123, v123, v146
	v_max_f32_e32 v123, 0x179abe15, v123
	v_rsq_f32_e32 v123, v123
	v_mul_f32_e32 v157, v103, v115
	s_waitcnt lgkmcnt(1)
	v_add_f32_e32 v136, v136, v139
	s_waitcnt lgkmcnt(0)
	v_add_f32_e32 v141, v141, v144
	v_mul_f32_e32 v178, v52, v157
	v_mul_f32_e32 v52, v100, v132
	v_max_f32_e32 v103, 0x179abe15, v124
	ds_bpermute_b32 v139, v173, v136
	ds_bpermute_b32 v144, v173, v141
	v_rsq_f32_e32 v103, v103
	s_waitcnt vmcnt(8)
	v_mul_f32_e32 v124, v108, v52
	v_mul_f32_e32 v118, v118, v123
	v_max_f32_e32 v115, 0x179abe15, v125
	v_mov_b32_dpp v123, v124 quad_perm:[1,0,3,2] row_mask:0xf bank_mask:0xf bound_ctrl:1
	v_fmac_f32_e32 v123, v108, v52
	v_rsq_f32_e32 v115, v115
	v_mul_f32_e32 v158, v133, v103
	v_add_f32_dpp v52, v123, v123 quad_perm:[2,3,0,1] row_mask:0xf bank_mask:0xf bound_ctrl:1
	v_mul_f32_e32 v103, v98, v126
	s_waitcnt lgkmcnt(1)
	v_add_f32_e32 v136, v136, v139
	v_add_f32_dpp v52, v52, v52 row_half_mirror row_mask:0xf bank_mask:0xf bound_ctrl:1
	s_waitcnt lgkmcnt(0)
	v_add_f32_e32 v139, v141, v144
	v_mul_f32_e32 v141, v108, v103
	v_add_f32_dpp v52, v52, v52 row_mirror row_mask:0xf bank_mask:0xf bound_ctrl:1
	ds_bpermute_b32 v123, v151, v52
	v_mov_b32_dpp v124, v141 quad_perm:[1,0,3,2] row_mask:0xf bank_mask:0xf bound_ctrl:1
	v_fmac_f32_e32 v124, v108, v103
	v_mul_f32_e32 v144, v138, v115
	v_mul_f32_e32 v150, v137, v144
	v_add_f32_dpp v103, v124, v124 quad_perm:[2,3,0,1] row_mask:0xf bank_mask:0xf bound_ctrl:1
	v_mul_f32_e32 v137, v92, v121
	v_mul_f32_e32 v146, v108, v137
	v_add_f32_dpp v103, v103, v103 row_half_mirror row_mask:0xf bank_mask:0xf bound_ctrl:1
	s_waitcnt lgkmcnt(0)
	v_add_f32_e32 v167, v52, v123
	v_mov_b32_dpp v52, v146 quad_perm:[1,0,3,2] row_mask:0xf bank_mask:0xf bound_ctrl:1
	v_add_f32_dpp v103, v103, v103 row_mirror row_mask:0xf bank_mask:0xf bound_ctrl:1
	ds_bpermute_b32 v124, v151, v103
	v_fmac_f32_e32 v52, v108, v137
	v_max_f32_e32 v125, 0x179abe15, v135
	v_max_f32_e32 v115, 0x179abe15, v134
	v_add_f32_dpp v52, v52, v52 quad_perm:[2,3,0,1] row_mask:0xf bank_mask:0xf bound_ctrl:1
	v_rsq_f32_e32 v125, v125
	v_rsq_f32_e32 v115, v115
	v_add_f32_dpp v52, v52, v52 row_half_mirror row_mask:0xf bank_mask:0xf bound_ctrl:1
	s_waitcnt lgkmcnt(0)
	v_add_f32_e32 v161, v103, v124
	v_mul_f32_e32 v135, v88, v116
	v_add_f32_dpp v52, v52, v52 row_mirror row_mask:0xf bank_mask:0xf bound_ctrl:1
	ds_bpermute_b32 v103, v151, v52
	v_mul_f32_e32 v133, v143, v125
	v_mul_f32_e32 v147, v140, v115
	v_mul_f32_e32 v140, v108, v135
	v_mul_f32_e32 v138, v142, v133
	v_mul_f32_e32 v142, v82, v113
	v_max_f32_e32 v125, 0x179abe15, v139
	v_mul_f32_e32 v139, v78, v99
	v_max_f32_e32 v115, 0x179abe15, v136
	v_mul_f32_e32 v136, v108, v142
	v_mul_f32_e32 v143, v108, v139
	v_mov_b32_dpp v123, v140 quad_perm:[1,0,3,2] row_mask:0xf bank_mask:0xf bound_ctrl:1
	v_fmac_f32_e32 v123, v108, v135
	v_mov_b32_dpp v135, v136 quad_perm:[1,0,3,2] row_mask:0xf bank_mask:0xf bound_ctrl:1
	s_waitcnt lgkmcnt(0)
	v_add_f32_e32 v159, v52, v103
	v_mov_b32_dpp v52, v143 quad_perm:[1,0,3,2] row_mask:0xf bank_mask:0xf bound_ctrl:1
	v_fmac_f32_e32 v135, v108, v142
	v_fmac_f32_e32 v52, v108, v139
	v_add_f32_dpp v123, v123, v123 quad_perm:[2,3,0,1] row_mask:0xf bank_mask:0xf bound_ctrl:1
	v_add_f32_dpp v135, v135, v135 quad_perm:[2,3,0,1] row_mask:0xf bank_mask:0xf bound_ctrl:1
	v_add_f32_dpp v52, v52, v52 quad_perm:[2,3,0,1] row_mask:0xf bank_mask:0xf bound_ctrl:1
	v_add_f32_dpp v123, v123, v123 row_half_mirror row_mask:0xf bank_mask:0xf bound_ctrl:1
	v_add_f32_dpp v135, v135, v135 row_half_mirror row_mask:0xf bank_mask:0xf bound_ctrl:1
	v_add_f32_dpp v52, v52, v52 row_half_mirror row_mask:0xf bank_mask:0xf bound_ctrl:1
	v_add_f32_dpp v123, v123, v123 row_mirror row_mask:0xf bank_mask:0xf bound_ctrl:1
	v_add_f32_dpp v135, v135, v135 row_mirror row_mask:0xf bank_mask:0xf bound_ctrl:1
	v_add_f32_dpp v52, v52, v52 row_mirror row_mask:0xf bank_mask:0xf bound_ctrl:1
	v_rsq_f32_e32 v115, v115
	v_rsq_f32_e32 v125, v125
	ds_bpermute_b32 v124, v151, v123
	ds_bpermute_b32 v136, v151, v135
	ds_bpermute_b32 v103, v151, v52
	v_mul_f32_e32 v154, v72, v89
	v_mul_f32_e32 v141, v68, v69
	v_mul_f32_e32 v134, v145, v115
	v_mul_f32_e32 v115, v149, v125
	v_mul_f32_e32 v155, v108, v154
	v_mul_f32_e32 v156, v108, v141
	v_mul_f32_e32 v125, v148, v115
	s_waitcnt lgkmcnt(2)
	v_add_f32_e32 v148, v123, v124
	s_waitcnt lgkmcnt(1)
	v_add_f32_e32 v145, v135, v136
	v_mov_b32_dpp v123, v155 quad_perm:[1,0,3,2] row_mask:0xf bank_mask:0xf bound_ctrl:1
	v_mov_b32_dpp v135, v156 quad_perm:[1,0,3,2] row_mask:0xf bank_mask:0xf bound_ctrl:1
	s_waitcnt lgkmcnt(0)
	v_add_f32_e32 v140, v52, v103
	v_mul_f32_e32 v52, v178, v158
	v_fmac_f32_e32 v123, v108, v154
	v_fmac_f32_e32 v135, v108, v141
	v_mov_b32_dpp v52, v52 quad_perm:[1,0,3,2] row_mask:0xf bank_mask:0xf bound_ctrl:1
	v_add_f32_dpp v123, v123, v123 quad_perm:[2,3,0,1] row_mask:0xf bank_mask:0xf bound_ctrl:1
	v_add_f32_dpp v135, v135, v135 quad_perm:[2,3,0,1] row_mask:0xf bank_mask:0xf bound_ctrl:1
	v_fmac_f32_e32 v52, v178, v158
	v_add_f32_dpp v123, v123, v123 row_half_mirror row_mask:0xf bank_mask:0xf bound_ctrl:1
	v_add_f32_dpp v135, v135, v135 row_half_mirror row_mask:0xf bank_mask:0xf bound_ctrl:1
	v_add_f32_dpp v52, v52, v52 quad_perm:[2,3,0,1] row_mask:0xf bank_mask:0xf bound_ctrl:1
	v_add_f32_dpp v123, v123, v123 row_mirror row_mask:0xf bank_mask:0xf bound_ctrl:1
	v_add_f32_dpp v137, v135, v135 row_mirror row_mask:0xf bank_mask:0xf bound_ctrl:1
	v_add_f32_dpp v52, v52, v52 row_half_mirror row_mask:0xf bank_mask:0xf bound_ctrl:1
	ds_bpermute_b32 v124, v151, v123
	ds_bpermute_b32 v139, v151, v137
	v_add_f32_dpp v52, v52, v52 row_mirror row_mask:0xf bank_mask:0xf bound_ctrl:1
	ds_bpermute_b32 v154, v151, v52
	v_mul_f32_e32 v103, v132, v158
	s_waitcnt lgkmcnt(2)
	v_add_f32_e32 v135, v123, v124
	s_waitcnt lgkmcnt(1)
	v_add_f32_e32 v123, v137, v139
	v_mov_b32_dpp v103, v103 quad_perm:[1,0,3,2] row_mask:0xf bank_mask:0xf bound_ctrl:1
	v_fmac_f32_e32 v103, v132, v158
	v_mul_f32_e32 v137, v150, v147
	v_mul_f32_e32 v139, v121, v147
	v_mul_f32_e32 v142, v138, v134
	v_add_f32_dpp v103, v103, v103 quad_perm:[2,3,0,1] row_mask:0xf bank_mask:0xf bound_ctrl:1
	s_waitcnt lgkmcnt(0)
	v_add_f32_e32 v171, v52, v154
	v_mov_b32_dpp v52, v137 quad_perm:[1,0,3,2] row_mask:0xf bank_mask:0xf bound_ctrl:1
	v_add_f32_dpp v103, v103, v103 row_half_mirror row_mask:0xf bank_mask:0xf bound_ctrl:1
	v_mov_b32_dpp v137, v139 quad_perm:[1,0,3,2] row_mask:0xf bank_mask:0xf bound_ctrl:1
	v_mov_b32_dpp v142, v142 quad_perm:[1,0,3,2] row_mask:0xf bank_mask:0xf bound_ctrl:1
	v_add_f32_dpp v103, v103, v103 row_mirror row_mask:0xf bank_mask:0xf bound_ctrl:1
	v_fmac_f32_e32 v137, v121, v147
	v_fmac_f32_e32 v142, v138, v134
	ds_bpermute_b32 v155, v151, v103
	v_add_f32_dpp v137, v137, v137 quad_perm:[2,3,0,1] row_mask:0xf bank_mask:0xf bound_ctrl:1
	v_add_f32_dpp v142, v142, v142 quad_perm:[2,3,0,1] row_mask:0xf bank_mask:0xf bound_ctrl:1
	v_fmac_f32_e32 v52, v150, v147
	v_add_f32_dpp v137, v137, v137 row_half_mirror row_mask:0xf bank_mask:0xf bound_ctrl:1
	v_add_f32_dpp v142, v142, v142 row_half_mirror row_mask:0xf bank_mask:0xf bound_ctrl:1
	v_add_f32_dpp v52, v52, v52 quad_perm:[2,3,0,1] row_mask:0xf bank_mask:0xf bound_ctrl:1
	v_add_f32_dpp v137, v137, v137 row_mirror row_mask:0xf bank_mask:0xf bound_ctrl:1
	v_add_f32_dpp v142, v142, v142 row_mirror row_mask:0xf bank_mask:0xf bound_ctrl:1
	v_add_f32_dpp v52, v52, v52 row_half_mirror row_mask:0xf bank_mask:0xf bound_ctrl:1
	ds_bpermute_b32 v139, v151, v137
	ds_bpermute_b32 v154, v151, v142
	v_add_f32_dpp v52, v52, v52 row_mirror row_mask:0xf bank_mask:0xf bound_ctrl:1
	s_waitcnt lgkmcnt(2)
	v_add_f32_e32 v169, v103, v155
	ds_bpermute_b32 v103, v151, v52
	v_mul_f32_e32 v174, v125, v118
	v_mul_f32_e32 v175, v89, v118
	s_waitcnt lgkmcnt(2)
	v_add_f32_e32 v163, v137, v139
	s_waitcnt lgkmcnt(1)
	v_add_f32_e32 v155, v142, v154
	v_mov_b32_dpp v137, v174 quad_perm:[1,0,3,2] row_mask:0xf bank_mask:0xf bound_ctrl:1
	v_mov_b32_dpp v142, v175 quad_perm:[1,0,3,2] row_mask:0xf bank_mask:0xf bound_ctrl:1
	v_mul_f32_e32 v143, v113, v134
	v_fmac_f32_e32 v137, v125, v118
	v_fmac_f32_e32 v142, v89, v118
	s_waitcnt lgkmcnt(0)
	v_add_f32_e32 v165, v52, v103
	v_mov_b32_dpp v52, v143 quad_perm:[1,0,3,2] row_mask:0xf bank_mask:0xf bound_ctrl:1
	v_add_f32_dpp v137, v137, v137 quad_perm:[2,3,0,1] row_mask:0xf bank_mask:0xf bound_ctrl:1
	v_add_f32_dpp v142, v142, v142 quad_perm:[2,3,0,1] row_mask:0xf bank_mask:0xf bound_ctrl:1
	v_fmac_f32_e32 v52, v113, v134
	v_add_f32_dpp v137, v137, v137 row_half_mirror row_mask:0xf bank_mask:0xf bound_ctrl:1
	v_add_f32_dpp v142, v142, v142 row_half_mirror row_mask:0xf bank_mask:0xf bound_ctrl:1
	v_add_f32_dpp v52, v52, v52 quad_perm:[2,3,0,1] row_mask:0xf bank_mask:0xf bound_ctrl:1
	v_add_f32_dpp v137, v137, v137 row_mirror row_mask:0xf bank_mask:0xf bound_ctrl:1
	v_add_f32_dpp v174, v142, v142 row_mirror row_mask:0xf bank_mask:0xf bound_ctrl:1
	v_add_f32_dpp v52, v52, v52 row_half_mirror row_mask:0xf bank_mask:0xf bound_ctrl:1
	ds_bpermute_b32 v139, v151, v137
	ds_bpermute_b32 v175, v151, v174
	v_add_f32_dpp v52, v52, v52 row_mirror row_mask:0xf bank_mask:0xf bound_ctrl:1
	ds_bpermute_b32 v103, v151, v52
	ds_bpermute_b32 v168, v173, v167
	s_waitcnt lgkmcnt(3)
	v_add_f32_e32 v142, v137, v139
	s_waitcnt lgkmcnt(2)
	v_add_f32_e32 v137, v174, v175
	v_lshlrev_b64 v[174:175], 8, v[96:97]
	v_or_b32_sdwa v174, v174, v111 dst_sel:DWORD dst_unused:UNUSED_PAD src0_sel:DWORD src1_sel:BYTE_0
	s_waitcnt lgkmcnt(1)
	v_add_f32_e32 v151, v52, v103
	v_lshl_add_u64 v[176:177], v[174:175], 2, s[14:15]
	v_lshlrev_b64 v[174:175], 1, v[174:175]
	ds_bpermute_b32 v162, v173, v161
	ds_bpermute_b32 v160, v173, v159
	ds_bpermute_b32 v149, v173, v148
	ds_bpermute_b32 v146, v173, v145
	ds_bpermute_b32 v141, v173, v140
	ds_bpermute_b32 v136, v173, v135
	ds_bpermute_b32 v124, v173, v123
	ds_bpermute_b32 v172, v173, v171
	ds_bpermute_b32 v170, v173, v169
	ds_bpermute_b32 v166, v173, v165
	ds_bpermute_b32 v164, v173, v163
	ds_bpermute_b32 v156, v173, v155
	ds_bpermute_b32 v154, v173, v151
	ds_bpermute_b32 v143, v173, v142
	ds_bpermute_b32 v139, v173, v137
	global_store_dword v[176:177], v120, off
	v_cvt_pk_bf16_f32 v100, v100, v53

	global_store_short v174, v100, s[26:27]
	v_cvt_pk_bf16_f32 v100, v132, v53

	v_bfe_u32 v52, v111, 6, 2
	global_store_short v174, v100, s[28:29]
	v_cvt_pk_bf16_f32 v100, v178, v53

	v_lshlrev_b32_e32 v52, 2, v52
	global_store_short v174, v100, s[30:31]
	v_xor_b32_e32 v100, 0x80000000, v157

	v_cmp_eq_u32_e32 vcc, 0, v102
	v_lshl_add_u64 v[102:103], s[22:23], 0, v[52:53]
	v_cvt_pk_bf16_f32 v100, v100, v53
	global_store_short v174, v100, s[34:35]
	v_lshl_add_u64 v[176:177], s[16:17], 0, v[174:175]

	v_cvt_pk_bf16_f32 v90, v90, v53
	global_store_short v[176:177], v90, off
	v_cvt_pk_bf16_f32 v84, v84, v53
	global_store_short v174, v84, s[18:19]
	s_and_saveexec_b64 s[4:5], vcc
	s_cbranch_execz .LBB0_303
	v_lshl_add_u64 v[96:97], v[96:97], 4, v[102:103]
	s_waitcnt lgkmcnt(14)
	v_add_f32_e32 v84, v167, v168
	global_store_dword v[96:97], v84, off
.LBB0_303:
	s_or_b64 exec, exec, s[4:5]
	v_add_f32_e32 v84, v104, v91
	v_mul_f32_e32 v84, 0xbfb8aa3b, v84
	v_exp_f32_e32 v84, v84
	v_lshl_add_u64 v[90:91], s[24:25], 0, v[52:53]
	v_lshlrev_b64 v[96:97], 8, v[94:95]
	v_or_b32_sdwa v96, v96, v111 dst_sel:DWORD dst_unused:UNUSED_PAD src0_sel:DWORD src1_sel:BYTE_0
	v_add_f32_e32 v84, 1.0, v84
	v_rcp_f32_e32 v84, v84
	s_waitcnt lgkmcnt(7)
	v_add_f32_e32 v132, v171, v172
	v_lshl_add_u64 v[172:173], v[96:97], 2, s[14:15]
	v_lshlrev_b64 v[96:97], 1, v[96:97]
	v_mul_f32_e32 v52, 0xbf1b4598, v84
	v_mul_f32_e32 v52, 0x3fb8aa3b, v52
	v_exp_f32_e32 v52, v52

	v_mul_f32_e32 v100, v127, v158
	global_store_dword v[172:173], v52, off
	v_cvt_pk_bf16_f32 v52, v98, v53
	global_store_short v96, v52, s[26:27]
	v_cvt_pk_bf16_f32 v52, v126, v53

	global_store_short v96, v52, s[28:29]
	v_cvt_pk_bf16_f32 v52, v100, v53

	global_store_short v96, v52, s[30:31]
	v_mul_f32_e32 v52, v120, v158
	v_fma_f32 v52, v157, v132, -v52

	v_cvt_pk_bf16_f32 v52, v52, v53
	global_store_short v96, v52, s[34:35]
	s_and_saveexec_b64 s[4:5], vcc
	s_cbranch_execz .LBB0_305
	s_waitcnt lgkmcnt(6)
	v_add_f32_e32 v52, v169, v170
	v_xor_b32_e32 v52, 0x80000000, v52
	v_lshl_add_u64 v[126:127], v[94:95], 4, v[90:91]
	global_store_dword v[126:127], v52, off
.LBB0_305:
	s_or_b64 exec, exec, s[4:5]
	v_cvt_pk_bf16_f32 v52, v122, v53

	global_store_short v96, v52, s[16:17]
	v_cvt_pk_bf16_f32 v52, v85, v53

	global_store_short v96, v52, s[18:19]
	s_and_saveexec_b64 s[4:5], vcc
	s_cbranch_execz .LBB0_307
	v_add_f32_e32 v52, v161, v162
	v_lshl_add_u64 v[84:85], v[94:95], 4, v[102:103]
	global_store_dword v[84:85], v52, off
.LBB0_307:
	s_or_b64 exec, exec, s[4:5]
	v_add_f32_e32 v52, v104, v74
	v_mul_f32_e32 v52, 0xbfb8aa3b, v52
	v_exp_f32_e32 v52, v52
	v_lshlrev_b64 v[84:85], 8, v[86:87]
	v_or_b32_sdwa v84, v84, v111 dst_sel:DWORD dst_unused:UNUSED_PAD src0_sel:DWORD src1_sel:BYTE_0
	v_lshl_add_u64 v[94:95], v[84:85], 2, s[14:15]
	v_add_f32_e32 v52, 1.0, v52
	v_rcp_f32_e32 v52, v52
	v_lshlrev_b64 v[84:85], 1, v[84:85]


	v_mul_f32_e32 v52, 0xbf1b4598, v52
	v_mul_f32_e32 v52, 0x3fb8aa3b, v52
	v_exp_f32_e32 v52, v52
	global_store_dword v[94:95], v52, off
	v_cvt_pk_bf16_f32 v74, v92, v53
	global_store_short v84, v74, s[26:27]
	v_cvt_pk_bf16_f32 v74, v121, v53
	global_store_short v84, v74, s[28:29]
	v_cvt_pk_bf16_f32 v74, v150, v53

	global_store_short v84, v74, s[30:31]
	v_xor_b32_e32 v74, 0x80000000, v144

	v_cvt_pk_bf16_f32 v74, v74, v53
	global_store_short v84, v74, s[34:35]
	v_lshl_add_u64 v[94:95], s[16:17], 0, v[84:85]

	v_cvt_pk_bf16_f32 v74, v117, v53
	global_store_short v[94:95], v74, off
	v_cvt_pk_bf16_f32 v64, v64, v53
	global_store_short v84, v64, s[18:19]
	s_and_saveexec_b64 s[4:5], vcc
	s_cbranch_execz .LBB0_309
	v_add_f32_e32 v64, v159, v160
	v_lshl_add_u64 v[84:85], v[86:87], 4, v[102:103]
	global_store_dword v[84:85], v64, off
.LBB0_309:
	s_or_b64 exec, exec, s[4:5]
	v_add_f32_e32 v64, v104, v75
	v_mul_f32_e32 v64, 0xbfb8aa3b, v64
	v_exp_f32_e32 v64, v64
	v_lshlrev_b64 v[74:75], 8, v[80:81]
	v_or_b32_sdwa v74, v74, v111 dst_sel:DWORD dst_unused:UNUSED_PAD src0_sel:DWORD src1_sel:BYTE_0
	v_lshl_add_u64 v[84:85], v[74:75], 2, s[14:15]
	v_add_f32_e32 v64, 1.0, v64
	v_rcp_f32_e32 v64, v64
	v_lshlrev_b64 v[74:75], 1, v[74:75]

	s_waitcnt lgkmcnt(5)
	v_add_f32_e32 v94, v165, v166
	v_mul_f32_e32 v64, 0xbf1b4598, v64
	v_mul_f32_e32 v64, 0x3fb8aa3b, v64
	v_exp_f32_e32 v64, v64
	v_mul_f32_e32 v52, v52, v147
	v_mul_f32_e32 v92, v119, v147
	v_fma_f32 v52, v144, v94, -v52
	global_store_dword v[84:85], v64, off
	v_cvt_pk_bf16_f32 v64, v88, v53

	global_store_short v74, v64, s[26:27]
	v_cvt_pk_bf16_f32 v64, v116, v53
	global_store_short v74, v64, s[28:29]

	v_cvt_pk_bf16_f32 v64, v92, v53
	global_store_short v74, v64, s[30:31]

	v_cvt_pk_bf16_f32 v52, v52, v53
	global_store_short v74, v52, s[34:35]
	s_and_saveexec_b64 s[4:5], vcc
	s_cbranch_execz .LBB0_311
	s_waitcnt lgkmcnt(4)
	v_add_f32_e32 v52, v163, v164
	v_xor_b32_e32 v52, 0x80000000, v52
	v_lshl_add_u64 v[84:85], v[80:81], 4, v[90:91]
	global_store_dword v[84:85], v52, off
.LBB0_311:
	s_or_b64 exec, exec, s[4:5]
	v_cvt_pk_bf16_f32 v52, v114, v53

	global_store_short v74, v52, s[16:17]
	v_cvt_pk_bf16_f32 v52, v65, v53

	global_store_short v74, v52, s[18:19]
	s_and_saveexec_b64 s[4:5], vcc
	s_cbranch_execz .LBB0_313
	v_add_f32_e32 v52, v148, v149
	v_lshl_add_u64 v[64:65], v[80:81], 4, v[102:103]
	global_store_dword v[64:65], v52, off
.LBB0_313:
	s_or_b64 exec, exec, s[4:5]
	v_add_f32_e32 v52, v104, v60
	v_mul_f32_e32 v52, 0xbfb8aa3b, v52
	v_exp_f32_e32 v52, v52
	v_lshlrev_b64 v[64:65], 8, v[76:77]
	v_or_b32_sdwa v64, v64, v111 dst_sel:DWORD dst_unused:UNUSED_PAD src0_sel:DWORD src1_sel:BYTE_0
	v_lshl_add_u64 v[74:75], v[64:65], 2, s[14:15]
	v_add_f32_e32 v52, 1.0, v52
	v_rcp_f32_e32 v52, v52
	v_lshlrev_b64 v[64:65], 1, v[64:65]


	v_mul_f32_e32 v52, 0xbf1b4598, v52
	v_mul_f32_e32 v52, 0x3fb8aa3b, v52
	v_exp_f32_e32 v52, v52
	global_store_dword v[74:75], v52, off
	v_cvt_pk_bf16_f32 v60, v82, v53
	global_store_short v64, v60, s[26:27]
	v_cvt_pk_bf16_f32 v60, v113, v53
	global_store_short v64, v60, s[28:29]
	v_cvt_pk_bf16_f32 v60, v138, v53

	global_store_short v64, v60, s[30:31]
	v_xor_b32_e32 v60, 0x80000000, v133

	v_cvt_pk_bf16_f32 v60, v60, v53
	global_store_short v64, v60, s[34:35]
	v_lshl_add_u64 v[74:75], s[16:17], 0, v[64:65]

	v_cvt_pk_bf16_f32 v60, v101, v53
	global_store_short v[74:75], v60, off
	v_cvt_pk_bf16_f32 v58, v58, v53
	global_store_short v64, v58, s[18:19]
	s_and_saveexec_b64 s[4:5], vcc
	s_cbranch_execz .LBB0_315
	v_add_f32_e32 v58, v145, v146
	v_lshl_add_u64 v[64:65], v[76:77], 4, v[102:103]
	global_store_dword v[64:65], v58, off
.LBB0_315:
	s_or_b64 exec, exec, s[4:5]
	v_add_f32_e32 v58, v104, v61
	v_mul_f32_e32 v58, 0xbfb8aa3b, v58
	v_exp_f32_e32 v58, v58
	v_lshlrev_b64 v[60:61], 8, v[70:71]
	v_or_b32_sdwa v60, v60, v111 dst_sel:DWORD dst_unused:UNUSED_PAD src0_sel:DWORD src1_sel:BYTE_0
	v_lshl_add_u64 v[64:65], v[60:61], 2, s[14:15]
	v_add_f32_e32 v58, 1.0, v58
	v_rcp_f32_e32 v58, v58
	v_lshlrev_b64 v[60:61], 1, v[60:61]

	s_waitcnt lgkmcnt(3)
	v_add_f32_e32 v77, v155, v156
	v_mul_f32_e32 v58, 0xbf1b4598, v58
	v_mul_f32_e32 v58, 0x3fb8aa3b, v58
	v_exp_f32_e32 v58, v58
	v_mul_f32_e32 v52, v52, v134
	v_mul_f32_e32 v76, v112, v134
	v_fma_f32 v52, v133, v77, -v52
	global_store_dword v[64:65], v58, off
	v_cvt_pk_bf16_f32 v58, v78, v53

	global_store_short v60, v58, s[26:27]
	v_cvt_pk_bf16_f32 v58, v99, v53
	global_store_short v60, v58, s[28:29]

	v_cvt_pk_bf16_f32 v58, v76, v53
	global_store_short v60, v58, s[30:31]

	v_cvt_pk_bf16_f32 v52, v52, v53
	global_store_short v60, v52, s[34:35]
	s_and_saveexec_b64 s[4:5], vcc
	s_cbranch_execz .LBB0_317
	s_waitcnt lgkmcnt(2)
	v_add_f32_e32 v52, v151, v154
	v_xor_b32_e32 v52, 0x80000000, v52
	v_lshl_add_u64 v[64:65], v[70:71], 4, v[90:91]
	global_store_dword v[64:65], v52, off
.LBB0_317:
	s_or_b64 exec, exec, s[4:5]
	v_cvt_pk_bf16_f32 v52, v93, v53

	global_store_short v60, v52, s[16:17]
	v_cvt_pk_bf16_f32 v52, v59, v53

	global_store_short v60, v52, s[18:19]
	s_and_saveexec_b64 s[4:5], vcc
	s_cbranch_execz .LBB0_319
	v_add_f32_e32 v52, v140, v141
	v_lshl_add_u64 v[58:59], v[70:71], 4, v[102:103]
	global_store_dword v[58:59], v52, off
.LBB0_319:
	s_or_b64 exec, exec, s[4:5]
	v_add_f32_e32 v52, v104, v56
	v_mul_f32_e32 v52, 0xbfb8aa3b, v52
	v_exp_f32_e32 v52, v52
	v_lshlrev_b64 v[58:59], 8, v[66:67]
	v_or_b32_sdwa v58, v58, v111 dst_sel:DWORD dst_unused:UNUSED_PAD src0_sel:DWORD src1_sel:BYTE_0
	v_lshl_add_u64 v[60:61], v[58:59], 2, s[14:15]
	v_add_f32_e32 v52, 1.0, v52
	v_rcp_f32_e32 v52, v52
	v_lshlrev_b64 v[58:59], 1, v[58:59]


	v_mul_f32_e32 v52, 0xbf1b4598, v52
	v_mul_f32_e32 v52, 0x3fb8aa3b, v52
	v_exp_f32_e32 v52, v52
	global_store_dword v[60:61], v52, off
	v_cvt_pk_bf16_f32 v56, v72, v53
	global_store_short v58, v56, s[26:27]
	v_cvt_pk_bf16_f32 v56, v89, v53
	global_store_short v58, v56, s[28:29]
	v_cvt_pk_bf16_f32 v56, v125, v53

	global_store_short v58, v56, s[30:31]
	v_xor_b32_e32 v56, 0x80000000, v115

	v_cvt_pk_bf16_f32 v56, v56, v53
	global_store_short v58, v56, s[34:35]
	v_lshl_add_u64 v[60:61], s[16:17], 0, v[58:59]

	v_cvt_pk_bf16_f32 v56, v79, v53
	global_store_short v[60:61], v56, off
	v_cvt_pk_bf16_f32 v54, v54, v53
	global_store_short v58, v54, s[18:19]
	s_and_saveexec_b64 s[4:5], vcc
	s_cbranch_execz .LBB0_321
	v_add_f32_e32 v54, v135, v136
	v_lshl_add_u64 v[58:59], v[66:67], 4, v[102:103]
	global_store_dword v[58:59], v54, off
.LBB0_321:
	s_or_b64 exec, exec, s[4:5]
	v_add_f32_e32 v54, v104, v57
	v_mul_f32_e32 v54, 0xbfb8aa3b, v54
	v_exp_f32_e32 v54, v54
	v_lshlrev_b64 v[56:57], 8, v[62:63]
	v_or_b32_sdwa v56, v56, v111 dst_sel:DWORD dst_unused:UNUSED_PAD src0_sel:DWORD src1_sel:BYTE_0
	v_lshl_add_u64 v[58:59], v[56:57], 2, s[14:15]
	v_add_f32_e32 v54, 1.0, v54
	v_rcp_f32_e32 v54, v54
	v_lshlrev_b64 v[56:57], 1, v[56:57]

	s_waitcnt lgkmcnt(1)
	v_add_f32_e32 v65, v142, v143
	v_mul_f32_e32 v54, 0xbf1b4598, v54
	v_mul_f32_e32 v54, 0x3fb8aa3b, v54
	v_exp_f32_e32 v54, v54
	v_mul_f32_e32 v52, v52, v118
	v_mul_f32_e32 v64, v83, v118
	v_fma_f32 v52, v115, v65, -v52
	global_store_dword v[58:59], v54, off
	v_cvt_pk_bf16_f32 v54, v68, v53

	global_store_short v56, v54, s[26:27]
	v_cvt_pk_bf16_f32 v54, v69, v53
	global_store_short v56, v54, s[28:29]

	v_cvt_pk_bf16_f32 v54, v64, v53
	global_store_short v56, v54, s[30:31]

	v_cvt_pk_bf16_f32 v52, v52, v53
	global_store_short v56, v52, s[34:35]
	s_and_saveexec_b64 s[4:5], vcc
	s_cbranch_execz .LBB0_323
	s_waitcnt lgkmcnt(0)
	v_add_f32_e32 v52, v137, v139
	v_xor_b32_e32 v52, 0x80000000, v52
	v_lshl_add_u64 v[58:59], v[62:63], 4, v[90:91]
	global_store_dword v[58:59], v52, off
.LBB0_323:
	s_or_b64 exec, exec, s[4:5]
	v_cvt_pk_bf16_f32 v52, v73, v53

	global_store_short v56, v52, s[16:17]
	v_cvt_pk_bf16_f32 v52, v55, v53

	global_store_short v56, v52, s[18:19]
	s_and_saveexec_b64 s[4:5], vcc
	s_cbranch_execz .LBB0_166
	v_add_f32_e32 v52, v123, v124
	v_lshl_add_u64 v[54:55], v[62:63], 4, v[102:103]
	global_store_dword v[54:55], v52, off
	s_branch .LBB0_166

.LBB0_1183:
	s_or_b64 exec, exec, s[44:45]
	v_lshl_add_u32 v68, v139, 2, 0
	ds_write_b32 v68, v69 offset:57600
	v_and_b32_e32 v68, 15, v139
	v_bfe_u32 v106, v139, 4, 2
	v_mul_u32_u24_e32 v71, 0xe10, v68
	v_and_b32_e32 v107, 0xffffff80, v70
	v_lshlrev_b32_e32 v70, 5, v106
	v_add3_u32 v94, 0, v71, v70
	v_add_u32_e32 v74, v94, v107
	s_waitcnt lgkmcnt(0)
	s_barrier
	ds_read_b128 v[70:73], v74 offset:2048
	ds_read_b128 v[74:77], v74 offset:2064
	s_waitcnt lgkmcnt(1)
	v_cvt_pk_bf16_f32 v70, v70, v71
	v_cvt_pk_bf16_f32 v71, v72, v73
	s_waitcnt lgkmcnt(0)
	v_cvt_pk_bf16_f32 v72, v74, v75
	v_cvt_pk_bf16_f32 v73, v76, v77
	v_lshl_add_u32 v108, v106, 9, 0
	v_mfma_f32_16x16x32_bf16 v[74:77], v[70:73], v[38:41], 0
	v_lshlrev_b32_e32 v109, 2, v68
	v_add_u32_e32 v78, v108, v109
	s_nop 5
	ds_add_f32 v78, v74 offset:57600
	ds_add_f32 v78, v75 offset:57728
	ds_add_f32 v78, v76 offset:57856
	ds_add_f32 v78, v77 offset:57984
	v_mfma_f32_16x16x32_bf16 v[70:73], v[70:73], v[62:65], 0
	s_nop 7
	ds_add_f32 v78, v70 offset:57664
	ds_add_f32 v78, v71 offset:57792
	ds_add_f32 v78, v72 offset:57920
	ds_add_f32 v78, v73 offset:58048
	s_waitcnt lgkmcnt(0)
	s_barrier
	ds_read_b128 v[70:73], v94 offset:3072
	ds_read_b128 v[74:77], v94 offset:3088
	s_waitcnt lgkmcnt(1)
	v_cvt_pk_bf16_f32 v70, v70, v71
	v_cvt_pk_bf16_f32 v71, v72, v73
	s_waitcnt lgkmcnt(0)
	v_cvt_pk_bf16_f32 v72, v74, v75
	v_cvt_pk_bf16_f32 v73, v76, v77
	ds_read_b128 v[74:77], v94 offset:3200
	ds_read_b128 v[78:81], v94 offset:3216
	s_waitcnt lgkmcnt(1)
	v_cvt_pk_bf16_f32 v74, v74, v75
	v_cvt_pk_bf16_f32 v75, v76, v77
	s_waitcnt lgkmcnt(0)
	v_cvt_pk_bf16_f32 v76, v78, v79
	v_cvt_pk_bf16_f32 v77, v80, v81
	ds_read_b128 v[78:81], v94 offset:3328
	ds_read_b128 v[82:85], v94 offset:3344
	s_waitcnt lgkmcnt(1)
	v_cvt_pk_bf16_f32 v78, v78, v79
	v_cvt_pk_bf16_f32 v79, v80, v81
	s_waitcnt lgkmcnt(0)
	v_cvt_pk_bf16_f32 v80, v82, v83
	v_cvt_pk_bf16_f32 v81, v84, v85
	ds_read_b128 v[82:85], v94 offset:3456
	ds_read_b128 v[86:89], v94 offset:3472
	v_mfma_f32_16x16x32_bf16 v[98:101], v[78:81], v[26:29], 0
	v_mad_i32_i24 v68, v68, s62, v94
	s_waitcnt lgkmcnt(1)
	v_cvt_pk_bf16_f32 v82, v82, v83
	v_mfma_f32_16x16x32_bf16 v[78:81], v[78:81], v[50:53], 0
	v_cvt_pk_bf16_f32 v83, v84, v85
	s_waitcnt lgkmcnt(0)
	v_cvt_pk_bf16_f32 v84, v86, v87
	v_cvt_pk_bf16_f32 v85, v88, v89
	v_mfma_f32_16x16x32_bf16 v[90:93], v[70:73], v[18:21], 0
	ds_read_b128 v[94:97], v68 offset:57600
	ds_read_b128 v[102:105], v68 offset:57616
	v_mad_u32_u24 v68, v106, s63, v108
	v_mfma_f32_16x16x32_bf16 v[70:73], v[70:73], v[42:45], 0
	s_waitcnt lgkmcnt(1)
	v_cvt_pk_bf16_f32 v94, v94, v95
	v_add3_u32 v68, v68, v107, v109
	v_cvt_pk_bf16_f32 v95, v96, v97
	v_mfma_f32_16x16x32_bf16 v[86:89], v[74:77], v[22:25], 0
	s_waitcnt lgkmcnt(0)
	v_cvt_pk_bf16_f32 v96, v102, v103
	v_cvt_pk_bf16_f32 v97, v104, v105
	v_add_u32_e32 v106, 0xe900, v68
	v_mfma_f32_16x16x32_bf16 v[74:77], v[74:77], v[46:49], 0
	s_ashr_i32 s37, s36, 31
	v_mfma_f32_16x16x32_bf16 v[98:101], v[82:85], v[30:33], v[98:101]
	v_mfma_f32_16x16x32_bf16 v[78:81], v[82:85], v[54:57], v[78:81]
	v_mfma_f32_16x16x32_bf16 v[102:105], v[94:97], v[34:37], 0
	v_mfma_f32_16x16x32_bf16 v[82:85], v[94:97], v[58:61], 0
	v_add_u32_e32 v94, 0xe800, v68
	ds_write2_b32 v94, v90, v70 offset0:64 offset1:80
	v_add_u32_e32 v70, 0x4000, v106
	ds_write2_b32 v70, v86, v74 offset1:16
	v_add_u32_e32 v70, 0x8000, v106
	s_nop 0
	ds_write2_b32 v70, v98, v78 offset1:16
	v_add_u32_e32 v70, 0xc000, v106
	ds_write2_b32 v70, v102, v82 offset1:16
	v_add_u32_e32 v70, 0xec00, v68
	ds_write2_b32 v70, v91, v71 offset0:64 offset1:80
	v_add_u32_e32 v70, 0x4400, v106
	ds_write2_b32 v70, v87, v75 offset1:16
	v_add_u32_e32 v70, 0x8400, v106
	ds_write2_b32 v70, v99, v79 offset1:16
	v_add_u32_e32 v70, 0xc400, v106
	ds_write2_b32 v70, v103, v83 offset1:16
	v_add_u32_e32 v70, 0xf000, v68
	ds_write2_b32 v70, v92, v72 offset0:64 offset1:80
	v_add_u32_e32 v70, 0x4800, v106
	v_add_u32_e32 v68, 0xf400, v68
	ds_write2_b32 v70, v88, v76 offset1:16
	v_add_u32_e32 v70, 0x8800, v106
	ds_write2_b32 v68, v93, v73 offset0:64 offset1:80
	v_add_u32_e32 v68, 0x4c00, v106
	v_ashrrev_i32_e32 v90, 8, v139
	ds_write2_b32 v70, v100, v80 offset1:16
	ds_write2_b32 v68, v89, v77 offset1:16
	v_add_u32_e32 v68, 0x8c00, v106
	v_lshlrev_b32_e32 v80, 3, v90
	ds_write2_b32 v68, v101, v81 offset1:16
	v_add_u32_e32 v68, 0xcc00, v106
	v_ashrrev_i32_e32 v81, 31, v80
	v_add_u32_e32 v70, 0xc800, v106
	ds_write2_b32 v68, v105, v85 offset1:16
	v_lshlrev_b32_sdwa v68, v138, v139 dst_sel:DWORD dst_unused:UNUSED_PAD src0_sel:DWORD src1_sel:BYTE_0
	v_lshl_add_u64 v[118:119], v[80:81], 0, s[36:37]
	ds_write2_b32 v70, v104, v84 offset1:16
	v_lshl_add_u64 v[124:125], s[20:21], 0, v[68:69]
	v_lshlrev_b64 v[70:71], 9, v[118:119]
	v_lshl_add_u64 v[70:71], v[124:125], 0, v[70:71]
	s_waitcnt lgkmcnt(0)
	s_barrier
	global_load_ushort v81, v[70:71], off
	v_lshlrev_b32_e32 v70, 13, v90
	v_lshlrev_b32_sdwa v96, v17, v139 dst_sel:DWORD dst_unused:UNUSED_PAD src0_sel:DWORD src1_sel:BYTE_0
	v_add3_u32 v70, 0, v70, v96
	v_add_u32_e32 v72, 0xe900, v70
	ds_read2st64_b32 v[120:121], v70 offset0:233 offset1:237
	ds_read2st64_b32 v[84:85], v72 offset0:64 offset1:68
	ds_read2st64_b32 v[106:107], v72 offset0:128 offset1:132
	ds_read2st64_b32 v[112:113], v72 offset0:192 offset1:196
	ds_read2st64_b32 v[100:101], v70 offset0:241 offset1:245
	ds_read2st64_b32 v[86:87], v72 offset0:72 offset1:76
	ds_read2st64_b32 v[92:93], v72 offset0:136 offset1:140
	ds_read2st64_b32 v[94:95], v72 offset0:200 offset1:204
	ds_read2st64_b32 v[82:83], v70 offset0:249 offset1:253
	ds_read2st64_b32 v[88:89], v72 offset0:80 offset1:84
	ds_read2st64_b32 v[76:77], v72 offset0:144 offset1:148
	ds_read2st64_b32 v[78:79], v72 offset0:208 offset1:212
	ds_read2st64_b32 v[74:75], v72 offset0:24 offset1:28
	ds_read2st64_b32 v[144:145], v72 offset0:88 offset1:92
	s_waitcnt vmcnt(6) lgkmcnt(13)
	v_add_f32_e32 v70, v132, v120
	v_mul_f32_e32 v70, 0xbfb8aa3b, v70
	v_exp_f32_e32 v91, v70
	v_mul_i32_i24_e32 v90, 0x7080, v90
	v_add3_u32 v90, 0, v90, v96
	ds_read2st64_b32 v[70:71], v72 offset0:152 offset1:156
	ds_read2st64_b32 v[72:73], v72 offset0:216 offset1:220
	v_add_f32_e32 v91, 1.0, v91
	v_rcp_f32_e32 v91, v91
	ds_read2st64_b32 v[126:127], v90 offset1:4
	ds_read_b32 v120, v90 offset:2048
	s_waitcnt vmcnt(5) lgkmcnt(14)
	v_add_f32_e32 v84, v133, v84
	v_mul_f32_e32 v84, 0xbfb8aa3b, v84
	v_mul_f32_e32 v90, 0xbf1b4598, v91
	s_waitcnt vmcnt(1)
	v_add_f32_e32 v91, v137, v112
	v_mul_f32_e32 v91, 0xbfb8aa3b, v91
	v_exp_f32_e32 v84, v84
	v_exp_f32_e32 v91, v91
	v_mul_f32_e32 v90, 0x3fb8aa3b, v90
	v_exp_f32_e32 v156, v90
	v_add_f32_e32 v84, 1.0, v84
	v_add_f32_e32 v90, 1.0, v91
	v_rcp_f32_e32 v90, v90
	v_rcp_f32_e32 v143, v84
	s_waitcnt lgkmcnt(1)
	v_mul_f32_e32 v160, v134, v127
	v_mul_f32_e32 v162, v160, v160
	v_and_b32_e32 v68, 63, v139
	s_waitcnt vmcnt(0)
	v_lshlrev_b32_e32 v81, 16, v81
	s_waitcnt lgkmcnt(0)
	v_sub_f32_e32 v81, v81, v120
	v_fmac_f32_e32 v120, v81, v90
	v_add_f32_e32 v81, -1.0, v143
	v_fma_f32 v81, v135, v81, 1.0
	v_mul_f32_e32 v164, v81, v127
	v_add_f32_e32 v81, v133, v85
	v_mul_f32_e32 v81, 0xbfb8aa3b, v81
	v_exp_f32_e32 v81, v81
	v_or_b32_e32 v90, 1, v80
	v_mul_lo_u32 v84, v90, s61
	v_add3_u32 v141, 0, v84, v96
	v_add_f32_e32 v81, 1.0, v81
	v_rcp_f32_e32 v163, v81
	ds_read2st64_b32 v[122:123], v141 offset1:4
	v_ashrrev_i32_e32 v91, 31, v90
	v_lshl_add_u64 v[116:117], v[90:91], 0, s[36:37]
	v_add_f32_e32 v81, -1.0, v163
	v_fma_f32 v81, v135, v81, 1.0
	s_waitcnt lgkmcnt(0)
	v_mul_f32_e32 v161, v81, v123
	v_add_f32_e32 v81, v133, v86
	v_mul_f32_e32 v81, 0xbfb8aa3b, v81
	v_exp_f32_e32 v81, v81
	v_lshlrev_b64 v[84:85], 9, v[116:117]
	v_lshl_add_u64 v[148:149], v[124:125], 0, v[84:85]
	v_or_b32_e32 v84, 2, v80
	v_ashrrev_i32_e32 v85, 31, v84
	v_add_f32_e32 v81, 1.0, v81
	v_lshl_add_u64 v[110:111], v[84:85], 0, s[36:37]
	v_add_u32_e32 v84, 16, v141
	v_rcp_f32_e32 v179, v81
	ds_read2st64_b32 v[114:115], v84 offset0:14 offset1:18
	v_lshlrev_b64 v[84:85], 9, v[110:111]
	v_lshl_add_u64 v[150:151], v[124:125], 0, v[84:85]
	v_add_f32_e32 v81, -1.0, v179
	v_fma_f32 v81, v135, v81, 1.0
	s_waitcnt lgkmcnt(0)
	v_mul_f32_e32 v154, v81, v115
	v_add_f32_e32 v81, v133, v87
	v_mul_f32_e32 v81, 0xbfb8aa3b, v81
	v_exp_f32_e32 v81, v81
	v_or_b32_e32 v84, 3, v80
	v_ashrrev_i32_e32 v85, 31, v84
	v_lshl_add_u64 v[104:105], v[84:85], 0, s[36:37]
	v_add_f32_e32 v81, 1.0, v81
	v_add_u32_e32 v84, 32, v141
	v_rcp_f32_e32 v147, v81
	ds_read2st64_b32 v[108:109], v84 offset0:28 offset1:32
	v_lshlrev_b64 v[84:85], 9, v[104:105]
	v_lshl_add_u64 v[158:159], v[124:125], 0, v[84:85]
	v_add_f32_e32 v81, -1.0, v147
	v_fma_f32 v81, v135, v81, 1.0
	s_waitcnt lgkmcnt(0)
	v_mul_f32_e32 v146, v81, v109
	v_add_f32_e32 v81, v133, v88
	v_mul_f32_e32 v81, 0xbfb8aa3b, v81
	v_exp_f32_e32 v81, v81
	v_or_b32_e32 v84, 4, v80
	v_ashrrev_i32_e32 v85, 31, v84
	v_lshl_add_u64 v[98:99], v[84:85], 0, s[36:37]
	v_add_f32_e32 v81, 1.0, v81
	v_add_u32_e32 v84, 48, v141
	v_rcp_f32_e32 v183, v81
	ds_read2st64_b32 v[102:103], v84 offset0:42 offset1:46
	v_lshlrev_b64 v[84:85], 9, v[98:99]
	v_lshl_add_u64 v[166:167], v[124:125], 0, v[84:85]
	v_add_f32_e32 v81, -1.0, v183
	v_fma_f32 v81, v135, v81, 1.0
	s_waitcnt lgkmcnt(0)
	v_mul_f32_e32 v142, v81, v103
	v_add_f32_e32 v81, v133, v89
	v_mul_f32_e32 v81, 0xbfb8aa3b, v81
	v_exp_f32_e32 v81, v81
	v_or_b32_e32 v84, 5, v80
	v_ashrrev_i32_e32 v85, 31, v84
	v_lshl_add_u64 v[90:91], v[84:85], 0, s[36:37]
	v_add_f32_e32 v81, 1.0, v81
	v_add_u32_e32 v84, 64, v141
	v_rcp_f32_e32 v140, v81
	ds_read2st64_b32 v[96:97], v84 offset0:56 offset1:60
	v_mul_f32_e32 v176, v134, v123
	v_lshlrev_b64 v[84:85], 9, v[90:91]
	v_add_f32_e32 v81, -1.0, v140
	v_fma_f32 v81, v135, v81, 1.0
	s_waitcnt lgkmcnt(0)
	v_mul_f32_e32 v123, v81, v97
	v_add_f32_e32 v81, v133, v144
	v_mul_f32_e32 v81, 0xbfb8aa3b, v81
	v_exp_f32_e32 v81, v81
	v_lshl_add_u64 v[168:169], v[124:125], 0, v[84:85]
	v_or_b32_e32 v84, 6, v80
	v_ashrrev_i32_e32 v85, 31, v84
	v_add_f32_e32 v81, 1.0, v81
	v_lshl_add_u64 v[86:87], v[84:85], 0, s[36:37]
	v_add_u32_e32 v84, 0x50, v141
	v_rcp_f32_e32 v144, v81
	ds_read2st64_b32 v[88:89], v84 offset0:70 offset1:74
	v_mul_f32_e32 v181, v134, v109
	v_mul_f32_e32 v186, v134, v97
	v_add_f32_e32 v81, -1.0, v144
	v_fma_f32 v81, v135, v81, 1.0
	s_waitcnt lgkmcnt(0)
	v_mul_f32_e32 v188, v134, v89
	v_mul_f32_e32 v109, v81, v89
	v_add_f32_e32 v89, v133, v145
	v_mul_f32_e32 v89, 0xbfb8aa3b, v89
	v_exp_f32_e32 v97, v89
	v_or_b32_e32 v80, 7, v80
	v_ashrrev_i32_e32 v81, 31, v80
	v_lshlrev_b64 v[84:85], 9, v[86:87]
	v_lshl_add_u64 v[80:81], v[80:81], 0, s[36:37]
	v_mul_f32_e32 v177, v176, v176
	v_lshl_add_u64 v[170:171], v[124:125], 0, v[84:85]
	v_add_u32_e32 v84, 0x60, v141
	v_add_f32_e32 v97, 1.0, v97
	v_lshlrev_b64 v[172:173], 9, v[80:81]
	v_mul_f32_e32 v178, v134, v115
	v_mul_f32_e32 v185, v134, v103
	ds_read2st64_b32 v[84:85], v84 offset0:84 offset1:88
	ds_read_b32 v174, v141 offset:2048
	ds_read_b32 v165, v141 offset:5648
	ds_read_b32 v155, v141 offset:9248
	ds_read_b32 v145, v141 offset:12848
	ds_read_b32 v127, v141 offset:16448
	ds_read_b32 v112, v141 offset:20048
	ds_read_b32 v89, v141 offset:23648
	v_rcp_f32_e32 v103, v97
	v_lshl_add_u64 v[124:125], v[124:125], 0, v[172:173]
	global_load_ushort v175, v[148:149], off
	global_load_ushort v173, v[150:151], off
	global_load_ushort v157, v[158:159], off
	s_nop 0
	global_load_ushort v151, v[166:167], off
	global_load_ushort v141, v[168:169], off
	global_load_ushort v115, v[170:171], off
	global_load_ushort v97, v[124:125], off
	v_and_b32_e32 v149, 64, v153
	v_mov_b32_dpp v150, v162 quad_perm:[1,0,3,2] row_mask:0xf bank_mask:0xf bound_ctrl:1
	v_mov_b32_dpp v159, v177 quad_perm:[1,0,3,2] row_mask:0xf bank_mask:0xf bound_ctrl:1
	v_xor_b32_e32 v148, 16, v153
	v_add_u32_e32 v149, 64, v149
	v_fmac_f32_e32 v150, v160, v160
	v_fmac_f32_e32 v159, v176, v176
	v_cmp_lt_i32_e32 vcc, v148, v149
	v_add_f32_dpp v150, v150, v150 quad_perm:[2,3,0,1] row_mask:0xf bank_mask:0xf bound_ctrl:1
	v_add_f32_dpp v159, v159, v159 quad_perm:[2,3,0,1] row_mask:0xf bank_mask:0xf bound_ctrl:1
	v_cndmask_b32_e32 v148, v153, v148, vcc
	v_add_f32_dpp v150, v150, v150 row_half_mirror row_mask:0xf bank_mask:0xf bound_ctrl:1
	v_add_f32_dpp v159, v159, v159 row_half_mirror row_mask:0xf bank_mask:0xf bound_ctrl:1
	v_lshlrev_b32_e32 v166, 2, v148
	v_add_f32_dpp v150, v150, v150 row_mirror row_mask:0xf bank_mask:0xf bound_ctrl:1
	v_add_f32_dpp v159, v159, v159 row_mirror row_mask:0xf bank_mask:0xf bound_ctrl:1
	ds_bpermute_b32 v158, v166, v150
	ds_bpermute_b32 v162, v166, v159
	v_xor_b32_e32 v148, 32, v153
	v_cmp_lt_i32_e32 vcc, v148, v149
	v_mul_f32_e32 v180, v178, v178
	v_mul_f32_e32 v182, v181, v181
	v_cndmask_b32_e32 v148, v153, v148, vcc
	v_lshlrev_b32_e32 v167, 2, v148
	s_waitcnt lgkmcnt(1)
	v_add_f32_e32 v148, v150, v158
	s_waitcnt lgkmcnt(0)
	v_add_f32_e32 v150, v159, v162
	v_mov_b32_dpp v159, v180 quad_perm:[1,0,3,2] row_mask:0xf bank_mask:0xf bound_ctrl:1
	v_mov_b32_dpp v168, v182 quad_perm:[1,0,3,2] row_mask:0xf bank_mask:0xf bound_ctrl:1
	v_fmac_f32_e32 v159, v178, v178
	v_fmac_f32_e32 v168, v181, v181
	v_mul_f32_e32 v184, v185, v185
	v_add_f32_dpp v159, v159, v159 quad_perm:[2,3,0,1] row_mask:0xf bank_mask:0xf bound_ctrl:1
	v_add_f32_dpp v168, v168, v168 quad_perm:[2,3,0,1] row_mask:0xf bank_mask:0xf bound_ctrl:1
	v_mov_b32_dpp v170, v184 quad_perm:[1,0,3,2] row_mask:0xf bank_mask:0xf bound_ctrl:1
	v_add_f32_dpp v159, v159, v159 row_half_mirror row_mask:0xf bank_mask:0xf bound_ctrl:1
	v_add_f32_dpp v168, v168, v168 row_half_mirror row_mask:0xf bank_mask:0xf bound_ctrl:1
	v_fmac_f32_e32 v170, v185, v185
	v_add_f32_dpp v159, v159, v159 row_mirror row_mask:0xf bank_mask:0xf bound_ctrl:1
	v_add_f32_dpp v168, v168, v168 row_mirror row_mask:0xf bank_mask:0xf bound_ctrl:1
	ds_bpermute_b32 v162, v166, v159
	ds_bpermute_b32 v169, v166, v168
	v_add_f32_dpp v170, v170, v170 quad_perm:[2,3,0,1] row_mask:0xf bank_mask:0xf bound_ctrl:1
	ds_bpermute_b32 v149, v167, v148
	ds_bpermute_b32 v158, v167, v150
	v_add_f32_dpp v170, v170, v170 row_half_mirror row_mask:0xf bank_mask:0xf bound_ctrl:1
	s_waitcnt lgkmcnt(3)
	v_add_f32_e32 v159, v159, v162
	s_waitcnt lgkmcnt(2)
	v_add_f32_e32 v168, v168, v169
	v_add_f32_dpp v170, v170, v170 row_mirror row_mask:0xf bank_mask:0xf bound_ctrl:1
	ds_bpermute_b32 v171, v166, v170
	ds_bpermute_b32 v162, v167, v159
	ds_bpermute_b32 v169, v167, v168
	v_add_f32_e32 v125, -1.0, v103
	v_mul_f32_e32 v187, v186, v186
	v_mul_f32_e32 v189, v188, v188
	v_mul_f32_e32 v124, v134, v85
	v_fma_f32 v125, v135, v125, 1.0
	s_waitcnt lgkmcnt(2)
	v_add_f32_e32 v170, v170, v171
	v_mul_f32_e32 v85, v125, v85
	v_mul_f32_e32 v125, v124, v124
	ds_bpermute_b32 v171, v167, v170
	v_add_f32_e32 v148, v148, v149
	v_add_f32_e32 v149, v150, v158
	s_waitcnt lgkmcnt(2)
	v_add_f32_e32 v150, v159, v162
	s_waitcnt lgkmcnt(1)
	v_add_f32_e32 v158, v168, v169
	v_mov_b32_dpp v162, v187 quad_perm:[1,0,3,2] row_mask:0xf bank_mask:0xf bound_ctrl:1
	v_mov_b32_dpp v169, v189 quad_perm:[1,0,3,2] row_mask:0xf bank_mask:0xf bound_ctrl:1
	v_fmac_f32_e32 v162, v186, v186
	v_fmac_f32_e32 v169, v188, v188
	v_mov_b32_dpp v125, v125 quad_perm:[1,0,3,2] row_mask:0xf bank_mask:0xf bound_ctrl:1
	v_max_f32_e32 v148, 0x179abe15, v148
	v_add_f32_dpp v162, v162, v162 quad_perm:[2,3,0,1] row_mask:0xf bank_mask:0xf bound_ctrl:1
	v_add_f32_dpp v169, v169, v169 quad_perm:[2,3,0,1] row_mask:0xf bank_mask:0xf bound_ctrl:1
	v_fmac_f32_e32 v125, v124, v124
	v_rsq_f32_e32 v148, v148
	v_add_f32_dpp v162, v162, v162 row_half_mirror row_mask:0xf bank_mask:0xf bound_ctrl:1
	v_add_f32_dpp v169, v169, v169 row_half_mirror row_mask:0xf bank_mask:0xf bound_ctrl:1
	v_add_f32_dpp v125, v125, v125 quad_perm:[2,3,0,1] row_mask:0xf bank_mask:0xf bound_ctrl:1
	v_add_f32_dpp v162, v162, v162 row_mirror row_mask:0xf bank_mask:0xf bound_ctrl:1
	v_add_f32_dpp v169, v169, v169 row_mirror row_mask:0xf bank_mask:0xf bound_ctrl:1
	v_add_f32_dpp v125, v125, v125 row_half_mirror row_mask:0xf bank_mask:0xf bound_ctrl:1
	s_waitcnt lgkmcnt(0)
	v_add_f32_e32 v159, v170, v171
	ds_bpermute_b32 v168, v166, v162
	ds_bpermute_b32 v170, v166, v169
	v_add_f32_dpp v125, v125, v125 row_mirror row_mask:0xf bank_mask:0xf bound_ctrl:1
	ds_bpermute_b32 v171, v166, v125
	v_mul_f32_e32 v189, v160, v148
	v_mul_f32_e32 v203, v143, v189
	v_max_f32_e32 v143, 0x179abe15, v149
	v_max_f32_e32 v150, 0x179abe15, v150
	v_rsq_f32_e32 v143, v143
	v_rsq_f32_e32 v150, v150
	s_waitcnt lgkmcnt(2)
	v_add_f32_e32 v162, v162, v168
	s_waitcnt lgkmcnt(1)
	v_add_f32_e32 v169, v169, v170
	ds_bpermute_b32 v168, v167, v162
	ds_bpermute_b32 v170, v167, v169
	s_waitcnt lgkmcnt(2)
	v_add_f32_e32 v125, v125, v171
	ds_bpermute_b32 v171, v167, v125
	v_mul_f32_e32 v190, v176, v143
	v_mul_f32_e32 v178, v178, v150
	v_max_f32_e32 v143, 0x179abe15, v158
	v_max_f32_e32 v150, 0x179abe15, v159
	v_rsq_f32_e32 v143, v143
	v_rsq_f32_e32 v150, v150
	s_waitcnt lgkmcnt(2)
	v_add_f32_e32 v162, v162, v168
	s_waitcnt lgkmcnt(1)
	v_add_f32_e32 v169, v169, v170
	s_waitcnt lgkmcnt(0)
	v_add_f32_e32 v125, v125, v171
	v_mul_f32_e32 v184, v179, v178
	v_mul_f32_e32 v179, v181, v143
	v_mul_f32_e32 v158, v185, v150
	v_max_f32_e32 v143, 0x179abe15, v162
	v_max_f32_e32 v150, 0x179abe15, v169
	v_rsq_f32_e32 v143, v143
	v_rsq_f32_e32 v150, v150
	v_max_f32_e32 v125, 0x179abe15, v125
	v_rsq_f32_e32 v125, v125
	v_mul_f32_e32 v148, v126, v164
	v_mul_f32_e32 v149, v136, v148
	v_mul_f32_e32 v162, v186, v143
	v_mul_f32_e32 v143, v188, v150
	v_mul_f32_e32 v150, v144, v143
	v_mul_f32_e32 v144, v124, v125
	v_mov_b32_dpp v124, v149 quad_perm:[1,0,3,2] row_mask:0xf bank_mask:0xf bound_ctrl:1
	v_fmac_f32_e32 v124, v136, v148
	v_mul_f32_e32 v160, v122, v161
	v_mul_f32_e32 v170, v136, v160
	v_add_f32_dpp v124, v124, v124 quad_perm:[2,3,0,1] row_mask:0xf bank_mask:0xf bound_ctrl:1
	v_mul_f32_e32 v171, v114, v154
	v_mul_f32_e32 v172, v136, v171
	v_add_f32_dpp v124, v124, v124 row_half_mirror row_mask:0xf bank_mask:0xf bound_ctrl:1
	v_mov_b32_dpp v148, v170 quad_perm:[1,0,3,2] row_mask:0xf bank_mask:0xf bound_ctrl:1
	v_fmac_f32_e32 v148, v136, v160
	v_add_f32_dpp v124, v124, v124 row_mirror row_mask:0xf bank_mask:0xf bound_ctrl:1
	ds_bpermute_b32 v125, v166, v124
	v_add_f32_dpp v148, v148, v148 quad_perm:[2,3,0,1] row_mask:0xf bank_mask:0xf bound_ctrl:1
	v_mul_f32_e32 v159, v108, v146
	v_mul_f32_e32 v176, v136, v159
	v_add_f32_dpp v148, v148, v148 row_half_mirror row_mask:0xf bank_mask:0xf bound_ctrl:1
	s_waitcnt lgkmcnt(0)
	v_add_f32_e32 v197, v124, v125
	v_mov_b32_dpp v124, v172 quad_perm:[1,0,3,2] row_mask:0xf bank_mask:0xf bound_ctrl:1
	v_fmac_f32_e32 v124, v136, v171
	v_add_f32_dpp v148, v148, v148 row_mirror row_mask:0xf bank_mask:0xf bound_ctrl:1
	ds_bpermute_b32 v149, v166, v148
	v_add_f32_dpp v124, v124, v124 quad_perm:[2,3,0,1] row_mask:0xf bank_mask:0xf bound_ctrl:1
	v_mul_f32_e32 v177, v102, v142
	v_mul_f32_e32 v169, v96, v123
	v_add_f32_dpp v124, v124, v124 row_half_mirror row_mask:0xf bank_mask:0xf bound_ctrl:1
	v_mul_f32_e32 v180, v136, v177
	v_mul_f32_e32 v182, v136, v169
	v_add_f32_dpp v124, v124, v124 row_mirror row_mask:0xf bank_mask:0xf bound_ctrl:1
	ds_bpermute_b32 v125, v166, v124
	s_waitcnt lgkmcnt(1)
	v_add_f32_e32 v191, v148, v149
	v_mov_b32_dpp v148, v176 quad_perm:[1,0,3,2] row_mask:0xf bank_mask:0xf bound_ctrl:1
	v_fmac_f32_e32 v148, v136, v159
	v_mov_b32_dpp v159, v180 quad_perm:[1,0,3,2] row_mask:0xf bank_mask:0xf bound_ctrl:1
	s_waitcnt lgkmcnt(0)
	v_add_f32_e32 v187, v124, v125
	v_mov_b32_dpp v124, v182 quad_perm:[1,0,3,2] row_mask:0xf bank_mask:0xf bound_ctrl:1
	v_fmac_f32_e32 v159, v136, v177
	v_fmac_f32_e32 v124, v136, v169
	v_add_f32_dpp v148, v148, v148 quad_perm:[2,3,0,1] row_mask:0xf bank_mask:0xf bound_ctrl:1
	v_add_f32_dpp v159, v159, v159 quad_perm:[2,3,0,1] row_mask:0xf bank_mask:0xf bound_ctrl:1
	v_add_f32_dpp v124, v124, v124 quad_perm:[2,3,0,1] row_mask:0xf bank_mask:0xf bound_ctrl:1
	v_add_f32_dpp v148, v148, v148 row_half_mirror row_mask:0xf bank_mask:0xf bound_ctrl:1
	v_add_f32_dpp v159, v159, v159 row_half_mirror row_mask:0xf bank_mask:0xf bound_ctrl:1
	v_add_f32_dpp v124, v124, v124 row_half_mirror row_mask:0xf bank_mask:0xf bound_ctrl:1
	v_add_f32_dpp v148, v148, v148 row_mirror row_mask:0xf bank_mask:0xf bound_ctrl:1
	v_add_f32_dpp v159, v159, v159 row_mirror row_mask:0xf bank_mask:0xf bound_ctrl:1
	v_add_f32_dpp v124, v124, v124 row_mirror row_mask:0xf bank_mask:0xf bound_ctrl:1
	ds_bpermute_b32 v149, v166, v148
	ds_bpermute_b32 v171, v166, v159
	ds_bpermute_b32 v125, v166, v124
	v_mul_f32_e32 v168, v183, v158
	v_mul_f32_e32 v183, v88, v109
	v_mul_f32_e32 v160, v84, v85
	v_mul_f32_e32 v185, v136, v183
	v_mul_f32_e32 v170, v136, v160
	s_waitcnt lgkmcnt(2)
	v_add_f32_e32 v180, v148, v149
	s_waitcnt lgkmcnt(1)
	v_add_f32_e32 v176, v159, v171
	v_mov_b32_dpp v148, v185 quad_perm:[1,0,3,2] row_mask:0xf bank_mask:0xf bound_ctrl:1
	v_mov_b32_dpp v159, v170 quad_perm:[1,0,3,2] row_mask:0xf bank_mask:0xf bound_ctrl:1
	s_waitcnt lgkmcnt(0)
	v_add_f32_e32 v169, v124, v125
	v_mul_f32_e32 v124, v203, v190
	v_fmac_f32_e32 v148, v136, v183
	v_fmac_f32_e32 v159, v136, v160
	v_mov_b32_dpp v124, v124 quad_perm:[1,0,3,2] row_mask:0xf bank_mask:0xf bound_ctrl:1
	v_add_f32_dpp v148, v148, v148 quad_perm:[2,3,0,1] row_mask:0xf bank_mask:0xf bound_ctrl:1
	v_add_f32_dpp v159, v159, v159 quad_perm:[2,3,0,1] row_mask:0xf bank_mask:0xf bound_ctrl:1
	v_fmac_f32_e32 v124, v203, v190
	v_add_f32_dpp v148, v148, v148 row_half_mirror row_mask:0xf bank_mask:0xf bound_ctrl:1
	v_add_f32_dpp v159, v159, v159 row_half_mirror row_mask:0xf bank_mask:0xf bound_ctrl:1
	v_add_f32_dpp v124, v124, v124 quad_perm:[2,3,0,1] row_mask:0xf bank_mask:0xf bound_ctrl:1
	v_add_f32_dpp v148, v148, v148 row_mirror row_mask:0xf bank_mask:0xf bound_ctrl:1
	v_add_f32_dpp v171, v159, v159 row_mirror row_mask:0xf bank_mask:0xf bound_ctrl:1
	v_add_f32_dpp v124, v124, v124 row_half_mirror row_mask:0xf bank_mask:0xf bound_ctrl:1
	ds_bpermute_b32 v149, v166, v148
	ds_bpermute_b32 v172, v166, v171
	v_mul_f32_e32 v125, v164, v190
	v_add_f32_dpp v124, v124, v124 row_mirror row_mask:0xf bank_mask:0xf bound_ctrl:1
	ds_bpermute_b32 v185, v166, v124
	v_mov_b32_dpp v125, v125 quad_perm:[1,0,3,2] row_mask:0xf bank_mask:0xf bound_ctrl:1
	v_fmac_f32_e32 v125, v164, v190
	s_waitcnt lgkmcnt(2)
	v_add_f32_e32 v159, v148, v149
	s_waitcnt lgkmcnt(1)
	v_add_f32_e32 v148, v171, v172
	v_add_f32_dpp v125, v125, v125 quad_perm:[2,3,0,1] row_mask:0xf bank_mask:0xf bound_ctrl:1
	v_mul_f32_e32 v171, v184, v179
	v_mul_f32_e32 v172, v154, v179
	v_add_f32_dpp v125, v125, v125 row_half_mirror row_mask:0xf bank_mask:0xf bound_ctrl:1
	v_mul_f32_e32 v182, v168, v162
	s_waitcnt lgkmcnt(0)
	v_add_f32_e32 v201, v124, v185
	v_add_f32_dpp v125, v125, v125 row_mirror row_mask:0xf bank_mask:0xf bound_ctrl:1
	ds_bpermute_b32 v186, v166, v125
	v_mov_b32_dpp v124, v171 quad_perm:[1,0,3,2] row_mask:0xf bank_mask:0xf bound_ctrl:1
	v_mov_b32_dpp v171, v172 quad_perm:[1,0,3,2] row_mask:0xf bank_mask:0xf bound_ctrl:1
	v_mov_b32_dpp v182, v182 quad_perm:[1,0,3,2] row_mask:0xf bank_mask:0xf bound_ctrl:1
	v_fmac_f32_e32 v124, v184, v179
	v_fmac_f32_e32 v171, v154, v179
	v_fmac_f32_e32 v182, v168, v162
	v_add_f32_dpp v124, v124, v124 quad_perm:[2,3,0,1] row_mask:0xf bank_mask:0xf bound_ctrl:1
	v_add_f32_dpp v171, v171, v171 quad_perm:[2,3,0,1] row_mask:0xf bank_mask:0xf bound_ctrl:1
	v_add_f32_dpp v182, v182, v182 quad_perm:[2,3,0,1] row_mask:0xf bank_mask:0xf bound_ctrl:1
	v_add_f32_dpp v124, v124, v124 row_half_mirror row_mask:0xf bank_mask:0xf bound_ctrl:1
	v_add_f32_dpp v171, v171, v171 row_half_mirror row_mask:0xf bank_mask:0xf bound_ctrl:1
	v_add_f32_dpp v182, v182, v182 row_half_mirror row_mask:0xf bank_mask:0xf bound_ctrl:1
	v_add_f32_dpp v124, v124, v124 row_mirror row_mask:0xf bank_mask:0xf bound_ctrl:1
	v_add_f32_dpp v171, v171, v171 row_mirror row_mask:0xf bank_mask:0xf bound_ctrl:1
	v_add_f32_dpp v182, v182, v182 row_mirror row_mask:0xf bank_mask:0xf bound_ctrl:1
	s_waitcnt lgkmcnt(0)
	v_add_f32_e32 v199, v125, v186
	ds_bpermute_b32 v125, v166, v124
	ds_bpermute_b32 v172, v166, v171
	ds_bpermute_b32 v185, v166, v182
	v_mul_f32_e32 v183, v142, v162
	v_mul_f32_e32 v204, v150, v144
	v_mul_f32_e32 v205, v109, v144
	s_waitcnt lgkmcnt(2)
	v_add_f32_e32 v195, v124, v125
	s_waitcnt lgkmcnt(1)
	v_add_f32_e32 v193, v171, v172
	s_waitcnt lgkmcnt(0)
	v_add_f32_e32 v185, v182, v185
	v_mov_b32_dpp v124, v183 quad_perm:[1,0,3,2] row_mask:0xf bank_mask:0xf bound_ctrl:1
	v_mov_b32_dpp v171, v204 quad_perm:[1,0,3,2] row_mask:0xf bank_mask:0xf bound_ctrl:1
	v_mov_b32_dpp v182, v205 quad_perm:[1,0,3,2] row_mask:0xf bank_mask:0xf bound_ctrl:1
	v_fmac_f32_e32 v124, v142, v162
	v_fmac_f32_e32 v171, v150, v144
	v_fmac_f32_e32 v182, v109, v144
	v_add_f32_dpp v124, v124, v124 quad_perm:[2,3,0,1] row_mask:0xf bank_mask:0xf bound_ctrl:1
	v_add_f32_dpp v171, v171, v171 quad_perm:[2,3,0,1] row_mask:0xf bank_mask:0xf bound_ctrl:1
	v_add_f32_dpp v182, v182, v182 quad_perm:[2,3,0,1] row_mask:0xf bank_mask:0xf bound_ctrl:1
	v_add_f32_dpp v124, v124, v124 row_half_mirror row_mask:0xf bank_mask:0xf bound_ctrl:1
	v_add_f32_dpp v171, v171, v171 row_half_mirror row_mask:0xf bank_mask:0xf bound_ctrl:1
	v_add_f32_dpp v182, v182, v182 row_half_mirror row_mask:0xf bank_mask:0xf bound_ctrl:1
	v_add_f32_dpp v124, v124, v124 row_mirror row_mask:0xf bank_mask:0xf bound_ctrl:1
	v_add_f32_dpp v171, v171, v171 row_mirror row_mask:0xf bank_mask:0xf bound_ctrl:1
	v_add_f32_dpp v204, v182, v182 row_mirror row_mask:0xf bank_mask:0xf bound_ctrl:1
	ds_bpermute_b32 v125, v166, v124
	ds_bpermute_b32 v172, v166, v171
	ds_bpermute_b32 v166, v166, v204
	ds_bpermute_b32 v198, v167, v197
	ds_bpermute_b32 v192, v167, v191
	s_waitcnt lgkmcnt(4)
	v_add_f32_e32 v182, v124, v125
	s_waitcnt lgkmcnt(3)
	v_add_f32_e32 v171, v171, v172
	s_waitcnt lgkmcnt(2)
	v_add_f32_e32 v166, v204, v166
	v_lshlrev_b64 v[204:205], 8, v[118:119]
	v_or_b32_sdwa v204, v204, v139 dst_sel:DWORD dst_unused:UNUSED_PAD src0_sel:DWORD src1_sel:BYTE_0
	v_lshl_add_u64 v[206:207], v[204:205], 2, s[14:15]
	v_lshlrev_b64 v[204:205], 1, v[204:205]
	ds_bpermute_b32 v188, v167, v187
	ds_bpermute_b32 v181, v167, v180
	ds_bpermute_b32 v177, v167, v176
	ds_bpermute_b32 v170, v167, v169
	ds_bpermute_b32 v160, v167, v159
	ds_bpermute_b32 v149, v167, v148
	ds_bpermute_b32 v202, v167, v201
	ds_bpermute_b32 v200, v167, v199
	ds_bpermute_b32 v196, v167, v195
	ds_bpermute_b32 v194, v167, v193
	ds_bpermute_b32 v186, v167, v185
	ds_bpermute_b32 v183, v167, v182
	ds_bpermute_b32 v172, v167, v171
	ds_bpermute_b32 v167, v167, v166
	global_store_dword v[206:207], v156, off
	v_cvt_pk_bf16_f32 v126, v126, v69

	global_store_short v204, v126, s[26:27]
	v_cvt_pk_bf16_f32 v126, v164, v69

	v_bfe_u32 v124, v139, 6, 2
	global_store_short v204, v126, s[28:29]
	v_cvt_pk_bf16_f32 v126, v203, v69

	v_cmp_eq_u32_e32 vcc, 0, v68
	v_lshlrev_b32_e32 v68, 2, v124
	global_store_short v204, v126, s[30:31]
	v_xor_b32_e32 v126, 0x80000000, v189

	v_lshl_add_u64 v[124:125], s[22:23], 0, v[68:69]
	v_cvt_pk_bf16_f32 v126, v126, v69
	global_store_short v204, v126, s[34:35]
	v_lshl_add_u64 v[206:207], s[16:17], 0, v[204:205]

	v_cvt_pk_bf16_f32 v120, v120, v69
	global_store_short v[206:207], v120, off
	v_cvt_pk_bf16_f32 v106, v106, v69
	global_store_short v204, v106, s[18:19]
	s_and_saveexec_b64 s[4:5], vcc
	s_cbranch_execz .LBB0_1185
	s_waitcnt lgkmcnt(14)
	v_add_f32_e32 v106, v197, v198
	v_lshl_add_u64 v[118:119], v[118:119], 4, v[124:125]
	global_store_dword v[118:119], v106, off
.LBB0_1185:
	s_or_b64 exec, exec, s[4:5]
	v_add_f32_e32 v106, v132, v121
	v_mul_f32_e32 v106, 0xbfb8aa3b, v106
	v_exp_f32_e32 v106, v106
	v_lshl_add_u64 v[118:119], s[24:25], 0, v[68:69]
	v_lshlrev_b64 v[120:121], 8, v[116:117]
	v_or_b32_sdwa v120, v120, v139 dst_sel:DWORD dst_unused:UNUSED_PAD src0_sel:DWORD src1_sel:BYTE_0
	v_add_f32_e32 v106, 1.0, v106
	v_rcp_f32_e32 v106, v106
	v_mul_f32_e32 v126, v163, v190
	s_waitcnt lgkmcnt(7)
	v_add_f32_e32 v163, v201, v202
	v_lshl_add_u64 v[202:203], v[120:121], 2, s[14:15]
	v_mul_f32_e32 v68, 0xbf1b4598, v106
	v_mul_f32_e32 v68, 0x3fb8aa3b, v68
	v_exp_f32_e32 v68, v68
	v_lshlrev_b64 v[120:121], 1, v[120:121]

	global_store_dword v[202:203], v68, off
	v_cvt_pk_bf16_f32 v68, v122, v69
	global_store_short v120, v68, s[26:27]
	v_cvt_pk_bf16_f32 v68, v161, v69

	global_store_short v120, v68, s[28:29]
	v_cvt_pk_bf16_f32 v68, v126, v69

	global_store_short v120, v68, s[30:31]
	v_mul_f32_e32 v68, v156, v190
	v_fma_f32 v68, v189, v163, -v68

	v_cvt_pk_bf16_f32 v68, v68, v69
	global_store_short v120, v68, s[34:35]
	s_and_saveexec_b64 s[4:5], vcc
	s_cbranch_execz .LBB0_1187
	s_waitcnt lgkmcnt(6)
	v_add_f32_e32 v68, v199, v200
	v_lshl_add_u64 v[198:199], v[116:117], 4, v[118:119]
	v_xor_b32_e32 v68, 0x80000000, v68
	global_store_dword v[198:199], v68, off
.LBB0_1187:
	s_or_b64 exec, exec, s[4:5]
	v_add_f32_e32 v68, v137, v113
	v_mul_f32_e32 v68, 0xbfb8aa3b, v68
	v_exp_f32_e32 v68, v68
	s_waitcnt vmcnt(18)
	v_lshlrev_b32_e32 v106, 16, v175
	v_sub_f32_e32 v106, v106, v174

	v_add_f32_e32 v68, 1.0, v68
	v_rcp_f32_e32 v68, v68
	s_nop 0
	v_fmac_f32_e32 v174, v68, v106
	v_cvt_pk_bf16_f32 v68, v174, v69
	global_store_short v120, v68, s[16:17]
	v_cvt_pk_bf16_f32 v68, v107, v69

	global_store_short v120, v68, s[18:19]
	s_and_saveexec_b64 s[4:5], vcc
	s_cbranch_execz .LBB0_1189
	v_add_f32_e32 v68, v191, v192
	v_lshl_add_u64 v[106:107], v[116:117], 4, v[124:125]
	global_store_dword v[106:107], v68, off
.LBB0_1189:
	s_or_b64 exec, exec, s[4:5]
	v_add_f32_e32 v68, v132, v100
	v_mul_f32_e32 v68, 0xbfb8aa3b, v68
	v_exp_f32_e32 v68, v68
	v_add_f32_e32 v94, v137, v94
	v_mul_f32_e32 v94, 0xbfb8aa3b, v94
	v_exp_f32_e32 v94, v94
	v_add_f32_e32 v68, 1.0, v68
	v_rcp_f32_e32 v68, v68
	v_lshlrev_b64 v[106:107], 8, v[110:111]
	v_add_f32_e32 v94, 1.0, v94
	v_rcp_f32_e32 v94, v94
	v_mul_f32_e32 v68, 0xbf1b4598, v68
	v_mul_f32_e32 v68, 0x3fb8aa3b, v68
	v_exp_f32_e32 v68, v68
	s_waitcnt vmcnt(19)
	v_lshlrev_b32_e32 v100, 16, v173
	v_or_b32_sdwa v106, v106, v139 dst_sel:DWORD dst_unused:UNUSED_PAD src0_sel:DWORD src1_sel:BYTE_0
	v_sub_f32_e32 v100, v100, v165
	v_lshl_add_u64 v[116:117], v[106:107], 2, s[14:15]
	v_lshlrev_b64 v[106:107], 1, v[106:107]
	v_fmac_f32_e32 v165, v94, v100
	global_store_dword v[116:117], v68, off
	v_cvt_pk_bf16_f32 v94, v114, v69

	global_store_short v106, v94, s[26:27]
	v_cvt_pk_bf16_f32 v94, v154, v69

	global_store_short v106, v94, s[28:29]
	v_cvt_pk_bf16_f32 v94, v184, v69

	global_store_short v106, v94, s[30:31]
	v_xor_b32_e32 v94, 0x80000000, v178

	v_cvt_pk_bf16_f32 v94, v94, v69
	global_store_short v106, v94, s[34:35]
	v_lshl_add_u64 v[116:117], s[16:17], 0, v[106:107]

	v_cvt_pk_bf16_f32 v94, v165, v69
	global_store_short v[116:117], v94, off
	v_cvt_pk_bf16_f32 v92, v92, v69
	global_store_short v106, v92, s[18:19]
	s_and_saveexec_b64 s[4:5], vcc
	s_cbranch_execz .LBB0_1191
	v_add_f32_e32 v92, v187, v188
	v_lshl_add_u64 v[106:107], v[110:111], 4, v[124:125]
	global_store_dword v[106:107], v92, off
.LBB0_1191:
	s_or_b64 exec, exec, s[4:5]
	v_add_f32_e32 v92, v132, v101
	v_mul_f32_e32 v92, 0xbfb8aa3b, v92
	v_exp_f32_e32 v92, v92
	v_lshlrev_b64 v[100:101], 8, v[104:105]
	v_or_b32_sdwa v100, v100, v139 dst_sel:DWORD dst_unused:UNUSED_PAD src0_sel:DWORD src1_sel:BYTE_0
	v_lshl_add_u64 v[106:107], v[100:101], 2, s[14:15]
	v_add_f32_e32 v92, 1.0, v92
	v_rcp_f32_e32 v92, v92
	v_lshlrev_b64 v[100:101], 1, v[100:101]

	s_waitcnt lgkmcnt(5)
	v_add_f32_e32 v113, v195, v196
	v_mul_f32_e32 v92, 0xbf1b4598, v92
	v_mul_f32_e32 v92, 0x3fb8aa3b, v92
	v_exp_f32_e32 v92, v92
	v_mul_f32_e32 v68, v68, v179
	v_mul_f32_e32 v94, v147, v179
	v_fma_f32 v68, v178, v113, -v68
	global_store_dword v[106:107], v92, off
	v_cvt_pk_bf16_f32 v92, v108, v69

	global_store_short v100, v92, s[26:27]
	v_cvt_pk_bf16_f32 v92, v146, v69
	global_store_short v100, v92, s[28:29]

	v_cvt_pk_bf16_f32 v92, v94, v69
	global_store_short v100, v92, s[30:31]

	v_cvt_pk_bf16_f32 v68, v68, v69
	global_store_short v100, v68, s[34:35]
	s_and_saveexec_b64 s[4:5], vcc
	s_cbranch_execz .LBB0_1193
	s_waitcnt lgkmcnt(4)
	v_add_f32_e32 v68, v193, v194
	v_lshl_add_u64 v[106:107], v[104:105], 4, v[118:119]
	v_xor_b32_e32 v68, 0x80000000, v68
	global_store_dword v[106:107], v68, off
.LBB0_1193:
	s_or_b64 exec, exec, s[4:5]
	v_add_f32_e32 v68, v137, v95
	v_mul_f32_e32 v68, 0xbfb8aa3b, v68
	v_exp_f32_e32 v68, v68
	s_waitcnt vmcnt(30)
	v_lshlrev_b32_e32 v92, 16, v157
	v_sub_f32_e32 v92, v92, v155

	v_add_f32_e32 v68, 1.0, v68
	v_rcp_f32_e32 v68, v68
	s_nop 0
	v_fmac_f32_e32 v155, v68, v92
	v_cvt_pk_bf16_f32 v68, v155, v69
	global_store_short v100, v68, s[16:17]
	v_cvt_pk_bf16_f32 v68, v93, v69

	global_store_short v100, v68, s[18:19]
	s_and_saveexec_b64 s[4:5], vcc
	s_cbranch_execz .LBB0_1195
	v_add_f32_e32 v68, v180, v181
	v_lshl_add_u64 v[92:93], v[104:105], 4, v[124:125]
	global_store_dword v[92:93], v68, off
.LBB0_1195:
	s_or_b64 exec, exec, s[4:5]
	v_add_f32_e32 v68, v132, v82
	v_mul_f32_e32 v68, 0xbfb8aa3b, v68
	v_exp_f32_e32 v68, v68
	v_add_f32_e32 v78, v137, v78
	v_mul_f32_e32 v78, 0xbfb8aa3b, v78
	v_exp_f32_e32 v78, v78
	v_add_f32_e32 v68, 1.0, v68
	v_rcp_f32_e32 v68, v68
	v_lshlrev_b64 v[92:93], 8, v[98:99]
	v_add_f32_e32 v78, 1.0, v78
	v_rcp_f32_e32 v78, v78
	v_mul_f32_e32 v68, 0xbf1b4598, v68
	v_mul_f32_e32 v68, 0x3fb8aa3b, v68
	v_exp_f32_e32 v68, v68
	s_waitcnt vmcnt(31)
	v_lshlrev_b32_e32 v82, 16, v151
	v_or_b32_sdwa v92, v92, v139 dst_sel:DWORD dst_unused:UNUSED_PAD src0_sel:DWORD src1_sel:BYTE_0
	v_sub_f32_e32 v82, v82, v145
	v_lshl_add_u64 v[94:95], v[92:93], 2, s[14:15]
	v_lshlrev_b64 v[92:93], 1, v[92:93]
	v_fmac_f32_e32 v145, v78, v82
	global_store_dword v[94:95], v68, off
	v_cvt_pk_bf16_f32 v78, v102, v69

	global_store_short v92, v78, s[26:27]
	v_cvt_pk_bf16_f32 v78, v142, v69

	global_store_short v92, v78, s[28:29]
	v_cvt_pk_bf16_f32 v78, v168, v69

	global_store_short v92, v78, s[30:31]
	v_xor_b32_e32 v78, 0x80000000, v158

	v_cvt_pk_bf16_f32 v78, v78, v69
	global_store_short v92, v78, s[34:35]
	v_lshl_add_u64 v[94:95], s[16:17], 0, v[92:93]

	v_cvt_pk_bf16_f32 v78, v145, v69
	global_store_short v[94:95], v78, off
	v_cvt_pk_bf16_f32 v76, v76, v69
	global_store_short v92, v76, s[18:19]
	s_and_saveexec_b64 s[4:5], vcc
	s_cbranch_execz .LBB0_1197
	v_add_f32_e32 v76, v176, v177
	v_lshl_add_u64 v[92:93], v[98:99], 4, v[124:125]
	global_store_dword v[92:93], v76, off
.LBB0_1197:
	s_or_b64 exec, exec, s[4:5]
	v_add_f32_e32 v76, v132, v83
	v_mul_f32_e32 v76, 0xbfb8aa3b, v76
	v_exp_f32_e32 v76, v76
	v_lshlrev_b64 v[82:83], 8, v[90:91]
	v_or_b32_sdwa v82, v82, v139 dst_sel:DWORD dst_unused:UNUSED_PAD src0_sel:DWORD src1_sel:BYTE_0
	v_lshl_add_u64 v[92:93], v[82:83], 2, s[14:15]
	v_add_f32_e32 v76, 1.0, v76
	v_rcp_f32_e32 v76, v76
	v_lshlrev_b64 v[82:83], 1, v[82:83]

	s_waitcnt lgkmcnt(3)
	v_add_f32_e32 v98, v185, v186
	v_mul_f32_e32 v76, 0xbf1b4598, v76
	v_mul_f32_e32 v76, 0x3fb8aa3b, v76
	v_exp_f32_e32 v76, v76
	v_mul_f32_e32 v68, v68, v162
	v_mul_f32_e32 v78, v140, v162
	v_fma_f32 v68, v158, v98, -v68
	global_store_dword v[92:93], v76, off
	v_cvt_pk_bf16_f32 v76, v96, v69

	global_store_short v82, v76, s[26:27]
	v_cvt_pk_bf16_f32 v76, v123, v69
	global_store_short v82, v76, s[28:29]

	v_cvt_pk_bf16_f32 v76, v78, v69
	global_store_short v82, v76, s[30:31]

	v_cvt_pk_bf16_f32 v68, v68, v69
	global_store_short v82, v68, s[34:35]
	s_and_saveexec_b64 s[4:5], vcc
	s_cbranch_execz .LBB0_1199
	s_waitcnt lgkmcnt(2)
	v_add_f32_e32 v68, v182, v183
	v_lshl_add_u64 v[92:93], v[90:91], 4, v[118:119]
	v_xor_b32_e32 v68, 0x80000000, v68
	global_store_dword v[92:93], v68, off
.LBB0_1199:
	s_or_b64 exec, exec, s[4:5]
	v_add_f32_e32 v68, v137, v79
	v_mul_f32_e32 v68, 0xbfb8aa3b, v68
	v_exp_f32_e32 v68, v68
	s_waitcnt vmcnt(42)
	v_lshlrev_b32_e32 v76, 16, v141
	v_sub_f32_e32 v76, v76, v127

	v_add_f32_e32 v68, 1.0, v68
	v_rcp_f32_e32 v68, v68
	s_nop 0
	v_fmac_f32_e32 v127, v68, v76
	v_cvt_pk_bf16_f32 v68, v127, v69
	global_store_short v82, v68, s[16:17]
	v_cvt_pk_bf16_f32 v68, v77, v69

	global_store_short v82, v68, s[18:19]
	s_and_saveexec_b64 s[4:5], vcc
	s_cbranch_execz .LBB0_1201
	v_add_f32_e32 v68, v169, v170
	v_lshl_add_u64 v[76:77], v[90:91], 4, v[124:125]
	global_store_dword v[76:77], v68, off
.LBB0_1201:
	s_or_b64 exec, exec, s[4:5]
	v_add_f32_e32 v68, v132, v74
	v_mul_f32_e32 v68, 0xbfb8aa3b, v68
	v_exp_f32_e32 v68, v68
	v_add_f32_e32 v72, v137, v72
	v_mul_f32_e32 v72, 0xbfb8aa3b, v72
	v_exp_f32_e32 v72, v72
	v_add_f32_e32 v68, 1.0, v68
	v_rcp_f32_e32 v68, v68
	v_lshlrev_b64 v[76:77], 8, v[86:87]
	v_add_f32_e32 v72, 1.0, v72
	v_rcp_f32_e32 v72, v72
	v_mul_f32_e32 v68, 0xbf1b4598, v68
	v_mul_f32_e32 v68, 0x3fb8aa3b, v68
	v_exp_f32_e32 v68, v68
	s_waitcnt vmcnt(43)
	v_lshlrev_b32_e32 v74, 16, v115
	v_or_b32_sdwa v76, v76, v139 dst_sel:DWORD dst_unused:UNUSED_PAD src0_sel:DWORD src1_sel:BYTE_0
	v_sub_f32_e32 v74, v74, v112
	v_lshl_add_u64 v[78:79], v[76:77], 2, s[14:15]
	v_lshlrev_b64 v[76:77], 1, v[76:77]
	v_fmac_f32_e32 v112, v72, v74
	global_store_dword v[78:79], v68, off
	v_cvt_pk_bf16_f32 v72, v88, v69

	global_store_short v76, v72, s[26:27]
	v_cvt_pk_bf16_f32 v72, v109, v69

	global_store_short v76, v72, s[28:29]
	v_cvt_pk_bf16_f32 v72, v150, v69

	global_store_short v76, v72, s[30:31]
	v_xor_b32_e32 v72, 0x80000000, v143

	v_cvt_pk_bf16_f32 v72, v72, v69
	global_store_short v76, v72, s[34:35]
	v_lshl_add_u64 v[78:79], s[16:17], 0, v[76:77]

	v_cvt_pk_bf16_f32 v72, v112, v69
	global_store_short v[78:79], v72, off
	v_cvt_pk_bf16_f32 v70, v70, v69
	global_store_short v76, v70, s[18:19]
	s_and_saveexec_b64 s[4:5], vcc
	s_cbranch_execz .LBB0_1203
	v_add_f32_e32 v70, v159, v160
	v_lshl_add_u64 v[76:77], v[86:87], 4, v[124:125]
	global_store_dword v[76:77], v70, off
.LBB0_1203:
	s_or_b64 exec, exec, s[4:5]
	v_add_f32_e32 v70, v132, v75
	v_mul_f32_e32 v70, 0xbfb8aa3b, v70
	v_exp_f32_e32 v70, v70
	v_lshlrev_b64 v[74:75], 8, v[80:81]
	v_or_b32_sdwa v74, v74, v139 dst_sel:DWORD dst_unused:UNUSED_PAD src0_sel:DWORD src1_sel:BYTE_0
	v_lshl_add_u64 v[76:77], v[74:75], 2, s[14:15]
	v_add_f32_e32 v70, 1.0, v70
	v_rcp_f32_e32 v70, v70
	v_lshlrev_b64 v[74:75], 1, v[74:75]

	s_waitcnt lgkmcnt(1)
	v_add_f32_e32 v82, v171, v172
	v_mul_f32_e32 v70, 0xbf1b4598, v70
	v_mul_f32_e32 v70, 0x3fb8aa3b, v70
	v_exp_f32_e32 v70, v70
	v_mul_f32_e32 v68, v68, v144
	v_mul_f32_e32 v72, v103, v144
	v_fma_f32 v68, v143, v82, -v68
	global_store_dword v[76:77], v70, off
	v_cvt_pk_bf16_f32 v70, v84, v69

	global_store_short v74, v70, s[26:27]
	v_cvt_pk_bf16_f32 v70, v85, v69
	global_store_short v74, v70, s[28:29]

	v_cvt_pk_bf16_f32 v70, v72, v69
	global_store_short v74, v70, s[30:31]

	v_cvt_pk_bf16_f32 v68, v68, v69
	global_store_short v74, v68, s[34:35]
	s_and_saveexec_b64 s[4:5], vcc
	s_cbranch_execz .LBB0_1205
	s_waitcnt lgkmcnt(0)
	v_add_f32_e32 v68, v166, v167
	v_lshl_add_u64 v[76:77], v[80:81], 4, v[118:119]
	v_xor_b32_e32 v68, 0x80000000, v68
	global_store_dword v[76:77], v68, off
.LBB0_1205:
	s_or_b64 exec, exec, s[4:5]
	v_add_f32_e32 v68, v137, v73
	v_mul_f32_e32 v68, 0xbfb8aa3b, v68
	v_exp_f32_e32 v68, v68
	s_waitcnt vmcnt(54)
	v_lshlrev_b32_e32 v70, 16, v97
	v_sub_f32_e32 v70, v70, v89

	v_add_f32_e32 v68, 1.0, v68
	v_rcp_f32_e32 v68, v68
	s_nop 0
	v_fmac_f32_e32 v89, v68, v70
	v_cvt_pk_bf16_f32 v68, v89, v69
	global_store_short v74, v68, s[16:17]
	v_cvt_pk_bf16_f32 v68, v71, v69

	global_store_short v74, v68, s[18:19]
	s_and_saveexec_b64 s[4:5], vcc
	s_cbranch_execz .LBB0_1048
	v_add_f32_e32 v68, v148, v149
	v_lshl_add_u64 v[70:71], v[80:81], 4, v[124:125]
	global_store_dword v[70:71], v68, off
	s_branch .LBB0_1048
